# combo33 + FFT next-unit input prefetch + FFT compiler pad removal (stack of two neutral FFT edits)
# speedup vs baseline: 1.0145x; 1.0072x over previous
.Lmy_fft_xskip:
.Lmy_fft_hj:
	v_mov_b32 v66, 0
	s_movk_i32 s5, 0x200
	v_add_u32_e32 v0, v66, v0
	v_cvt_f32_i32_e32 v68, v0
	v_ashrrev_i32_e32 v66, 5, v0
	v_lshlrev_b32_e32 v67, 3, v0
	v_lshlrev_b32_e32 v66, 3, v66
	v_add3_u32 v171, 0, v66, v67
	v_add_u32_e32 v216, 0x10800, v171
	v_mul_f32_e32 v0, 0x38800000, v68
	v_sin_f32_e32 v67, v0
	v_cos_f32_e32 v66, v0
	v_xor_b32_e32 v68, 0x80000000, v67
	v_mov_b32_e32 v69, v67
	v_pk_mul_f32 v[70:71], v[68:69], v[66:67] op_sel:[0,1] op_sel_hi:[1,0]
	v_pk_fma_f32 v[70:71], v[66:67], v[66:67], v[70:71] op_sel_hi:[1,0,1]
	v_pk_mul_f32 v[74:75], v[68:69], v[70:71] op_sel:[0,1] op_sel_hi:[1,0]
	v_pk_fma_f32 v[74:75], v[70:71], v[66:67], v[74:75] op_sel_hi:[1,0,1]
	v_pk_mul_f32 v[78:79], v[68:69], v[74:75] op_sel:[0,1] op_sel_hi:[1,0]
	v_pk_fma_f32 v[78:79], v[74:75], v[66:67], v[78:79] op_sel_hi:[1,0,1]
	v_pk_mul_f32 v[82:83], v[68:69], v[78:79] op_sel:[0,1] op_sel_hi:[1,0]
	v_pk_fma_f32 v[82:83], v[78:79], v[66:67], v[82:83] op_sel_hi:[1,0,1]
	v_pk_mul_f32 v[86:87], v[68:69], v[82:83] op_sel:[0,1] op_sel_hi:[1,0]
	s_waitcnt vmcnt(31)
	v_lshlrev_b32_e32 v126, 16, v105
	v_pk_fma_f32 v[86:87], v[82:83], v[66:67], v[86:87] op_sel_hi:[1,0,1]
	s_waitcnt vmcnt(30)
	v_lshlrev_b32_e32 v127, 16, v127
	v_pk_mul_f32 v[90:91], v[68:69], v[86:87] op_sel:[0,1] op_sel_hi:[1,0]
	s_waitcnt vmcnt(29)
	v_lshlrev_b32_e32 v129, 16, v128
	v_pk_fma_f32 v[90:91], v[86:87], v[66:67], v[90:91] op_sel_hi:[1,0,1]
	s_waitcnt vmcnt(24)
	v_lshlrev_b32_e32 v128, 16, v134
	v_pk_mul_f32 v[94:95], v[68:69], v[90:91] op_sel:[0,1] op_sel_hi:[1,0]
	v_lshlrev_b32_e32 v130, 16, v130
	v_pk_fma_f32 v[94:95], v[90:91], v[66:67], v[94:95] op_sel_hi:[1,0,1]
	v_lshlrev_b32_e32 v131, 16, v131
	v_pk_mul_f32 v[98:99], v[68:69], v[94:95] op_sel:[0,1] op_sel_hi:[1,0]
	v_lshlrev_b32_e32 v132, 16, v132
	v_pk_fma_f32 v[98:99], v[94:95], v[66:67], v[98:99] op_sel_hi:[1,0,1]
	v_lshlrev_b32_e32 v133, 16, v133
	v_pk_mul_f32 v[102:103], v[68:69], v[98:99] op_sel:[0,1] op_sel_hi:[1,0]
	s_waitcnt vmcnt(22)
	v_lshlrev_b32_e32 v135, 16, v135
	v_pk_fma_f32 v[102:103], v[98:99], v[66:67], v[102:103] op_sel_hi:[1,0,1]
	v_lshlrev_b32_e32 v134, 16, v136
	v_pk_mul_f32 v[108:109], v[68:69], v[102:103] op_sel:[0,1] op_sel_hi:[1,0]
	s_waitcnt vmcnt(21)
	v_lshlrev_b32_e32 v136, 16, v137
	v_pk_fma_f32 v[108:109], v[102:103], v[66:67], v[108:109] op_sel_hi:[1,0,1]
	s_waitcnt vmcnt(20)
	v_lshlrev_b32_e32 v137, 16, v138
	v_pk_mul_f32 v[112:113], v[68:69], v[108:109] op_sel:[0,1] op_sel_hi:[1,0]
	s_waitcnt vmcnt(19)
	v_lshlrev_b32_e32 v138, 16, v139
	s_waitcnt vmcnt(18)
	v_lshlrev_b32_e32 v139, 16, v140
	s_waitcnt vmcnt(17)
	v_lshlrev_b32_e32 v140, 16, v141
	s_waitcnt vmcnt(16)
	v_lshlrev_b32_e32 v141, 16, v142
	v_pk_fma_f32 v[112:113], v[108:109], v[66:67], v[112:113] op_sel_hi:[1,0,1]
	v_pk_add_f32 v[142:143], v[126:127], 0 op_sel_hi:[1,0]
	v_pk_add_f32 v[144:145], v[128:129], 0 op_sel_hi:[1,0]
	v_pk_mul_f32 v[146:147], v[128:129], s[36:37]
	v_pk_add_f32 v[148:149], v[130:131], 0 op_sel_hi:[1,0]
	v_pk_mul_f32 v[150:151], v[130:131], s[16:17]
	v_pk_add_f32 v[152:153], v[132:133], 0 op_sel_hi:[1,0]
	v_pk_mul_f32 v[154:155], v[132:133], s[38:39]
	v_pk_add_f32 v[156:157], v[134:135], 0 op_sel_hi:[1,0]
	v_xor_b32_e32 v159, 0x80000000, v134
	v_mov_b32_e32 v158, v135
	v_pk_add_f32 v[134:135], v[136:137], 0 op_sel_hi:[1,0]
	v_pk_mul_f32 v[160:161], v[136:137], s[38:39]
	v_pk_add_f32 v[162:163], v[138:139], 0 op_sel_hi:[1,0]
	v_pk_mul_f32 v[164:165], v[138:139], s[16:17]
	v_pk_add_f32 v[166:167], v[140:141], 0 op_sel_hi:[1,0]
	v_pk_mul_f32 v[168:169], v[140:141], s[36:37]
	v_pk_mul_f32 v[116:117], v[68:69], v[112:113] op_sel:[0,1] op_sel_hi:[1,0]
	v_pk_fma_f32 v[128:129], v[128:129], s[6:7], v[146:147] op_sel:[0,0,1] op_sel_hi:[1,0,0]
	v_pk_fma_f32 v[130:131], v[130:131], s[10:11], v[150:151] op_sel:[0,0,1] op_sel_hi:[1,0,0]
	v_pk_fma_f32 v[132:133], v[132:133], s[14:15], v[154:155] op_sel:[0,0,1] op_sel_hi:[1,0,0]
	v_pk_fma_f32 v[136:137], v[136:137], s[4:5], v[160:161] op_sel:[0,0,1] op_sel_hi:[1,0,0]
	v_pk_fma_f32 v[138:139], v[138:139], s[8:9], v[164:165] op_sel:[0,0,1] op_sel_hi:[1,0,0]
	v_pk_fma_f32 v[140:141], v[140:141], s[12:13], v[168:169] op_sel:[0,0,1] op_sel_hi:[1,0,0]
	v_pk_add_f32 v[146:147], v[142:143], v[156:157]
	v_pk_add_f32 v[150:151], v[144:145], v[134:135]
	v_pk_add_f32 v[134:135], v[144:145], v[134:135] neg_lo:[0,1] neg_hi:[0,1]
	v_pk_add_f32 v[144:145], v[148:149], v[162:163]
	v_pk_add_f32 v[160:161], v[148:149], v[162:163] op_sel:[1,1] op_sel_hi:[0,0] neg_lo:[0,1] neg_hi:[1,0]
	v_pk_add_f32 v[154:155], v[152:153], v[166:167]
	v_pk_add_f32 v[152:153], v[152:153], v[166:167] neg_lo:[0,1] neg_hi:[0,1]
	v_pk_fma_f32 v[116:117], v[112:113], v[66:67], v[116:117] op_sel_hi:[1,0,1]
	v_pk_add_f32 v[142:143], v[142:143], v[156:157] neg_lo:[0,1] neg_hi:[0,1]
	v_pk_add_f32 v[156:157], v[158:159], v[126:127]
	v_pk_add_f32 v[126:127], v[126:127], v[158:159] neg_lo:[0,1] neg_hi:[0,1]
	v_pk_mul_f32 v[158:159], v[134:135], s[16:17]
	v_pk_mul_f32 v[148:149], v[152:153], s[16:17]
	v_pk_add_f32 v[162:163], v[128:129], v[136:137]
	v_pk_add_f32 v[128:129], v[128:129], v[136:137] neg_lo:[0,1] neg_hi:[0,1]
	v_pk_add_f32 v[136:137], v[130:131], v[138:139]
	v_pk_add_f32 v[130:131], v[130:131], v[138:139] neg_lo:[0,1] neg_hi:[0,1]
	v_pk_add_f32 v[138:139], v[132:133], v[140:141]
	v_pk_add_f32 v[132:133], v[132:133], v[140:141] neg_lo:[0,1] neg_hi:[0,1]
	v_pk_add_f32 v[140:141], v[146:147], v[144:145]
	v_pk_add_f32 v[144:145], v[146:147], v[144:145] neg_lo:[0,1] neg_hi:[0,1]
	v_pk_add_f32 v[146:147], v[150:151], v[154:155]
	v_pk_add_f32 v[150:151], v[150:151], v[154:155] neg_lo:[0,1] neg_hi:[0,1]
	v_pk_mul_f32 v[120:121], v[68:69], v[116:117] op_sel:[0,1] op_sel_hi:[1,0]
	v_pk_fma_f32 v[134:135], v[134:135], s[10:11], v[158:159] op_sel:[0,0,1] op_sel_hi:[1,0,0]
	v_pk_fma_f32 v[148:149], v[152:153], s[8:9], v[148:149] op_sel:[0,0,1] op_sel_hi:[1,0,0]
	v_pk_mul_f32 v[152:153], v[128:129], s[16:17]
	v_xor_b32_e32 v155, 0x80000000, v130
	v_mov_b32_e32 v154, v131
	v_pk_mul_f32 v[130:131], v[132:133], s[16:17]
	v_xor_b32_e32 v159, 0x80000000, v150
	v_mov_b32_e32 v158, v151
	v_pk_add_f32 v[150:151], v[142:143], v[160:161]
	v_pk_add_f32 v[142:143], v[142:143], v[160:161] neg_lo:[0,1] neg_hi:[0,1]
	v_pk_add_f32 v[160:161], v[156:157], v[136:137]
	v_pk_add_f32 v[136:137], v[156:157], v[136:137] neg_lo:[0,1] neg_hi:[0,1]
	v_pk_add_f32 v[156:157], v[162:163], v[138:139]
	v_pk_add_f32 v[138:139], v[162:163], v[138:139] neg_lo:[0,1] neg_hi:[0,1]
	v_mov_b32_e32 v0, v67
	v_pk_fma_f32 v[120:121], v[116:117], v[66:67], v[120:121] op_sel_hi:[1,0,1]
	v_pk_add_f32 v[162:163], v[140:141], v[146:147]
	v_pk_add_f32 v[140:141], v[140:141], v[146:147] neg_lo:[0,1] neg_hi:[0,1]
	v_pk_fma_f32 v[128:129], v[128:129], s[10:11], v[152:153] op_sel:[0,0,1] op_sel_hi:[1,0,0]
	v_pk_fma_f32 v[130:131], v[132:133], s[8:9], v[130:131] op_sel:[0,0,1] op_sel_hi:[1,0,0]
	v_pk_add_f32 v[132:133], v[134:135], v[148:149]
	v_pk_add_f32 v[134:135], v[134:135], v[148:149] neg_lo:[0,1] neg_hi:[0,1]
	v_xor_b32_e32 v147, 0x80000000, v138
	v_mov_b32_e32 v146, v139
	v_pk_add_f32 v[152:153], v[160:161], v[156:157]
	v_pk_mul_f32 v[68:69], v[68:69], v[120:121] op_sel:[0,1] op_sel_hi:[1,0]
	v_pk_add_f32 v[138:139], v[126:127], v[154:155]
	v_pk_add_f32 v[126:127], v[126:127], v[154:155] neg_lo:[0,1] neg_hi:[0,1]
	v_pk_add_f32 v[148:149], v[144:145], v[158:159]
	v_pk_add_f32 v[144:145], v[144:145], v[158:159] neg_lo:[0,1] neg_hi:[0,1]
	v_pk_add_f32 v[154:155], v[160:161], v[156:157] neg_lo:[0,1] neg_hi:[0,1]
	v_pk_mul_f32 v[96:97], v[140:141], v[94:95] op_sel:[1,1] op_sel_hi:[0,1] neg_hi:[0,1]
	v_xor_b32_e32 v157, 0x80000000, v134
	v_mov_b32_e32 v156, v135
	v_pk_add_f32 v[134:135], v[128:129], v[130:131]
	v_pk_add_f32 v[128:129], v[128:129], v[130:131] neg_lo:[0,1] neg_hi:[0,1]
	v_pk_add_f32 v[130:131], v[150:151], v[132:133]
	v_pk_add_f32 v[132:133], v[150:151], v[132:133] neg_lo:[0,1] neg_hi:[0,1]
	v_pk_add_f32 v[150:151], v[136:137], v[146:147]
	v_pk_add_f32 v[136:137], v[136:137], v[146:147] neg_lo:[0,1] neg_hi:[0,1]
	v_pk_mul_f32 v[146:147], v[0:1], v[152:153] op_sel:[0,1] op_sel_hi:[0,0] neg_hi:[1,0]
	v_pk_add_f32 v[92:93], v[90:91], 0 neg_lo:[1,1] neg_hi:[1,1]
	v_pk_fma_f32 v[68:69], v[120:121], v[66:67], v[68:69] op_sel_hi:[1,0,1]
	v_pk_mul_f32 v[80:81], v[148:149], v[78:79] op_sel:[1,1] op_sel_hi:[0,1] neg_hi:[0,1]
	v_pk_fma_f32 v[94:95], v[140:141], v[94:95], v[96:97] op_sel_hi:[1,0,1]
	v_pk_mul_f32 v[96:97], v[154:155], v[98:99] op_sel:[1,1] op_sel_hi:[0,1] neg_hi:[0,1]
	v_pk_mul_f32 v[100:101], v[144:145], v[112:113] op_sel:[1,1] op_sel_hi:[0,1] neg_hi:[0,1]
	v_xor_b32_e32 v115, 0x80000000, v128
	v_mov_b32_e32 v114, v129
	v_pk_add_f32 v[128:129], v[142:143], v[156:157]
	v_pk_add_f32 v[140:141], v[142:143], v[156:157] neg_lo:[0,1] neg_hi:[0,1]
	v_pk_add_f32 v[142:143], v[138:139], v[134:135]
	v_pk_fma_f32 v[66:67], v[152:153], v[66:67], v[146:147] op_sel_hi:[1,0,1]
	v_pk_mul_f32 v[72:73], v[130:131], v[70:71] op_sel:[1,1] op_sel_hi:[0,1] neg_hi:[0,1]
	v_mov_b32_e32 v92, v91
	v_pk_add_f32 v[110:111], v[108:109], 0 neg_lo:[1,1] neg_hi:[1,1]
	v_pk_add_f32 v[118:119], v[116:117], 0 neg_lo:[1,1] neg_hi:[1,1]
	v_pk_add_f32 v[122:123], v[120:121], 0 neg_lo:[1,1] neg_hi:[1,1]
	v_pk_add_f32 v[124:125], v[68:69], 0 neg_lo:[1,1] neg_hi:[1,1]
	ds_write_b64 v171, v[162:163]
	v_pk_fma_f32 v[78:79], v[148:149], v[78:79], v[80:81] op_sel_hi:[1,0,1]
	v_pk_mul_f32 v[80:81], v[150:151], v[82:83] op_sel:[1,1] op_sel_hi:[0,1] neg_hi:[0,1]
	v_pk_fma_f32 v[84:85], v[154:155], v[98:99], v[96:97] op_sel_hi:[1,0,1]
	v_pk_mul_f32 v[96:97], v[132:133], v[102:103] op_sel:[1,1] op_sel_hi:[0,1] neg_hi:[0,1]
	v_pk_add_f32 v[106:107], v[126:127], v[114:115]
	ds_write_b64 v171, v[66:67] offset:8448
	v_pk_fma_f32 v[66:67], v[130:131], v[70:71], v[72:73] op_sel_hi:[1,0,1]
	v_pk_mul_f32 v[70:71], v[142:143], v[74:75] op_sel:[1,1] op_sel_hi:[0,1] neg_hi:[0,1]
	v_mov_b32_e32 v110, v109
	v_mov_b32_e32 v118, v117
	v_mov_b32_e32 v122, v121
	v_mov_b32_e32 v124, v69
	v_pk_add_f32 v[134:135], v[138:139], v[134:135] neg_lo:[0,1] neg_hi:[0,1]
	v_pk_fma_f32 v[98:99], v[144:145], v[112:113], v[100:101] op_sel_hi:[1,0,1]
	v_pk_add_f32 v[112:113], v[126:127], v[114:115] neg_lo:[0,1] neg_hi:[0,1]
	v_pk_mul_f32 v[76:77], v[128:129], v[86:87] op_sel:[1,1] op_sel_hi:[0,1] neg_hi:[0,1]
	ds_write_b64 v171, v[66:67] offset:16896
	v_pk_fma_f32 v[66:67], v[142:143], v[74:75], v[70:71] op_sel_hi:[1,0,1]
	v_pk_mul_f32 v[74:75], v[106:107], v[92:93] op_sel:[1,0] op_sel_hi:[0,1]
	s_mov_b64 s[48:49], 0
	s_and_b64 vcc, exec, vcc
	v_pk_mul_f32 v[100:101], v[136:137], v[118:119] op_sel:[1,0] op_sel_hi:[0,1]
	v_pk_fma_f32 v[72:73], v[150:151], v[82:83], v[80:81] op_sel_hi:[1,0,1]
	v_pk_fma_f32 v[80:81], v[132:133], v[102:103], v[96:97] op_sel_hi:[1,0,1]
	v_pk_mul_f32 v[82:83], v[134:135], v[110:111] op_sel:[1,0] op_sel_hi:[0,1]
	v_pk_mul_f32 v[96:97], v[140:141], v[122:123] op_sel:[1,0] op_sel_hi:[0,1]
	v_pk_fma_f32 v[70:71], v[128:129], v[86:87], v[76:77] op_sel_hi:[1,0,1]
	v_pk_mul_f32 v[86:87], v[112:113], v[124:125] op_sel:[1,0] op_sel_hi:[0,1]
	ds_write_b64 v171, v[66:67] offset:25344
	ds_write_b64 v171, v[78:79] offset:33792
	ds_write_b64 v171, v[72:73] offset:42240
	ds_write_b64 v171, v[70:71] offset:50688
	v_pk_fma_f32 v[66:67], v[106:107], v[90:91], v[74:75] op_sel_hi:[1,0,1]
	v_pk_fma_f32 v[88:89], v[136:137], v[116:117], v[100:101] op_sel_hi:[1,0,1]
	v_pk_fma_f32 v[76:77], v[134:135], v[108:109], v[82:83] op_sel_hi:[1,0,1]
	v_pk_fma_f32 v[82:83], v[140:141], v[120:121], v[96:97] op_sel_hi:[1,0,1]
	v_pk_fma_f32 v[68:69], v[112:113], v[68:69], v[86:87] op_sel_hi:[1,0,1]
	ds_write_b64 v171, v[66:67] offset:59136
	ds_write_b64 v216, v[94:95]
	ds_write_b64 v216, v[84:85] offset:8448
	ds_write_b64 v216, v[80:81] offset:16896
	ds_write_b64 v216, v[76:77] offset:25344
	ds_write_b64 v216, v[98:99] offset:33792
	ds_write_b64 v216, v[88:89] offset:42240
	ds_write_b64 v216, v[82:83] offset:50688
	ds_write_b64 v216, v[68:69] offset:59136
	s_cbranch_vccz .LBB0_362
	s_waitcnt lgkmcnt(0)
	s_barrier
	v_mov_b32 v0, 0
	s_mov_b32 s5, s14
	v_add_u32_e32 v74, v0, v170
	v_lshlrev_b32_e32 v0, 5, v74
	v_and_b32_e32 v71, 0xfffffc00, v0
	v_and_b32_e32 v70, 31, v74
	v_lshlrev_b32_e32 v78, 3, v71
	v_lshlrev_b32_e32 v79, 3, v70
	v_or_b32_e32 v67, 32, v71
	v_ashrrev_i32_e32 v67, 2, v67
	v_add_u32_e32 v67, 0, v67
	v_add3_u32 v114, v67, v78, v79
	v_ashrrev_i32_e32 v66, 2, v71
	v_add_u32_e32 v66, 0, v66
	v_add3_u32 v66, v66, v78, v79
	v_mov_b32_e32 v222, v114
	ds_read_b64 v[66:67], v66
	ds_read_b64 v[68:69], v222 offset:256
	ds_read_b64 v[72:73], v222 offset:520
	ds_read_b64 v[76:77], v222 offset:784
	ds_read_b64 v[80:81], v222 offset:1048
	ds_read_b64 v[82:83], v222 offset:1312
	ds_read_b64 v[116:117], v222 offset:1576
	ds_read_b64 v[118:119], v222 offset:1840
	ds_read_b64 v[120:121], v222 offset:2104
	ds_read_b64 v[122:123], v222 offset:2368
	ds_read_b64 v[124:125], v222 offset:2632
	ds_read_b64 v[126:127], v222 offset:2896
	ds_read_b64 v[128:129], v222 offset:3160
	ds_read_b64 v[130:131], v222 offset:3424
	ds_read_b64 v[132:133], v222 offset:3688
	ds_read_b64 v[134:135], v222 offset:3952
	ds_read_b64 v[136:137], v222 offset:4216
	ds_read_b64 v[138:139], v222 offset:4480
	ds_read_b64 v[140:141], v222 offset:4744
	ds_read_b64 v[142:143], v222 offset:5008
	s_waitcnt lgkmcnt(3)
	v_pk_add_f32 v[168:169], v[66:67], v[136:137]
	v_pk_add_f32 v[66:67], v[66:67], v[136:137] neg_lo:[0,1] neg_hi:[0,1]
	s_waitcnt lgkmcnt(2)
	v_pk_add_f32 v[136:137], v[68:69], v[138:139]
	v_pk_add_f32 v[68:69], v[68:69], v[138:139] neg_lo:[0,1] neg_hi:[0,1]
	v_pk_mul_f32 v[138:139], v[68:69], s[18:19]
	v_pk_fma_f32 v[68:69], v[68:69], s[20:21], v[138:139] op_sel:[0,0,1] op_sel_hi:[1,0,0]
	s_waitcnt lgkmcnt(1)
	v_pk_add_f32 v[138:139], v[72:73], v[140:141]
	v_pk_add_f32 v[72:73], v[72:73], v[140:141] neg_lo:[0,1] neg_hi:[0,1]
	v_pk_mul_f32 v[140:141], v[72:73], s[4:5]
	ds_read_b64 v[144:145], v222 offset:5272
	ds_read_b64 v[146:147], v222 offset:5536
	ds_read_b64 v[148:149], v222 offset:5800
	ds_read_b64 v[150:151], v222 offset:6064
	v_pk_fma_f32 v[72:73], v[72:73], s[6:7], v[140:141] op_sel:[0,0,1] op_sel_hi:[1,0,0]
	s_waitcnt lgkmcnt(4)
	v_pk_add_f32 v[140:141], v[76:77], v[142:143]
	v_pk_add_f32 v[76:77], v[76:77], v[142:143] neg_lo:[0,1] neg_hi:[0,1]
	v_pk_mul_f32 v[142:143], v[76:77], s[22:23]
	v_pk_fma_f32 v[76:77], v[76:77], s[24:25], v[142:143] op_sel:[0,0,1] op_sel_hi:[1,0,0]
	s_waitcnt lgkmcnt(3)
	v_pk_add_f32 v[142:143], v[80:81], v[144:145]
	v_pk_add_f32 v[80:81], v[80:81], v[144:145] neg_lo:[0,1] neg_hi:[0,1]
	s_mov_b32 s9, s10
	v_pk_mul_f32 v[144:145], v[80:81], s[8:9]
	v_pk_fma_f32 v[80:81], v[80:81], s[10:11], v[144:145] op_sel:[0,0,1] op_sel_hi:[1,0,0]
	s_waitcnt lgkmcnt(2)
	v_pk_add_f32 v[144:145], v[82:83], v[146:147]
	v_pk_add_f32 v[82:83], v[82:83], v[146:147] neg_lo:[0,1] neg_hi:[0,1]
	s_mov_b32 s27, s24
	v_pk_mul_f32 v[146:147], v[82:83], s[26:27]
	s_mov_b32 s0, s23
	v_pk_fma_f32 v[82:83], v[82:83], s[0:1], v[146:147] op_sel:[0,0,1] op_sel_hi:[1,0,0]
	s_waitcnt lgkmcnt(1)
	v_pk_add_f32 v[146:147], v[116:117], v[148:149]
	v_pk_add_f32 v[116:117], v[116:117], v[148:149] neg_lo:[0,1] neg_hi:[0,1]
	s_mov_b32 s13, s6
	v_pk_mul_f32 v[148:149], v[116:117], s[12:13]
	ds_read_b64 v[152:153], v222 offset:6328
	ds_read_b64 v[154:155], v222 offset:6592
	ds_read_b64 v[156:157], v222 offset:6856
	ds_read_b64 v[158:159], v222 offset:7120
	v_pk_fma_f32 v[116:117], v[116:117], s[14:15], v[148:149] op_sel:[0,0,1] op_sel_hi:[1,0,0]
	s_waitcnt lgkmcnt(4)
	v_pk_add_f32 v[148:149], v[118:119], v[150:151]
	v_pk_add_f32 v[118:119], v[118:119], v[150:151] neg_lo:[0,1] neg_hi:[0,1]
	s_mov_b32 s35, s20
	v_pk_mul_f32 v[150:151], v[118:119], s[34:35]
	s_mov_b32 s48, s19
	v_pk_fma_f32 v[118:119], v[118:119], s[48:49], v[150:151] op_sel:[0,0,1] op_sel_hi:[1,0,0]
	s_waitcnt lgkmcnt(3)
	v_pk_add_f32 v[150:151], v[120:121], v[152:153]
	v_pk_add_f32 v[152:153], v[120:121], v[152:153] op_sel:[1,1] op_sel_hi:[0,0] neg_lo:[0,1] neg_hi:[1,0]
	s_waitcnt lgkmcnt(2)
	v_pk_add_f32 v[120:121], v[122:123], v[154:155]
	v_pk_add_f32 v[122:123], v[122:123], v[154:155] neg_lo:[0,1] neg_hi:[0,1]
	v_pk_mul_f32 v[154:155], v[122:123], s[34:35]
	v_pk_fma_f32 v[122:123], v[122:123], s[18:19], v[154:155] op_sel:[0,0,1] op_sel_hi:[1,0,0]
	s_waitcnt lgkmcnt(1)
	v_pk_add_f32 v[154:155], v[124:125], v[156:157]
	v_pk_add_f32 v[124:125], v[124:125], v[156:157] neg_lo:[0,1] neg_hi:[0,1]
	v_pk_mul_f32 v[156:157], v[124:125], s[12:13]
	ds_read_b64 v[160:161], v222 offset:7384
	ds_read_b64 v[162:163], v222 offset:7648
	ds_read_b64 v[164:165], v222 offset:7912
	ds_read_b64 v[166:167], v222 offset:8176
	v_pk_fma_f32 v[124:125], v[124:125], s[4:5], v[156:157] op_sel:[0,0,1] op_sel_hi:[1,0,0]
	s_waitcnt lgkmcnt(4)
	v_pk_add_f32 v[156:157], v[126:127], v[158:159]
	v_pk_add_f32 v[126:127], v[126:127], v[158:159] neg_lo:[0,1] neg_hi:[0,1]
	v_lshlrev_b32_e32 v70, 4, v70
	v_pk_mul_f32 v[158:159], v[126:127], s[26:27]
	v_cvt_f32_u32_e32 v75, v70
	v_pk_fma_f32 v[126:127], v[126:127], s[22:23], v[158:159] op_sel:[0,0,1] op_sel_hi:[1,0,0]
	s_waitcnt lgkmcnt(3)
	v_pk_add_f32 v[158:159], v[128:129], v[160:161]
	v_pk_add_f32 v[128:129], v[128:129], v[160:161] neg_lo:[0,1] neg_hi:[0,1]
	v_and_b32_e32 v74, 0x1fffffe0, v74
	v_pk_mul_f32 v[160:161], v[128:129], s[8:9]
	v_mul_f32_e32 v115, 0x38800000, v75
	v_pk_fma_f32 v[128:129], v[128:129], s[8:9], v[160:161] op_sel:[0,0,1] op_sel_hi:[1,0,0]
	s_waitcnt lgkmcnt(2)
	v_pk_add_f32 v[160:161], v[130:131], v[162:163]
	v_pk_add_f32 v[130:131], v[130:131], v[162:163] neg_lo:[0,1] neg_hi:[0,1]
	v_lshl_add_u32 v74, v74, 3, 0
	v_pk_mul_f32 v[162:163], v[130:131], s[22:23]
	v_sin_f32_e32 v75, v115
	v_pk_fma_f32 v[130:131], v[130:131], s[26:27], v[162:163] op_sel:[0,0,1] op_sel_hi:[1,0,0]
	s_waitcnt lgkmcnt(1)
	v_pk_add_f32 v[162:163], v[132:133], v[164:165]
	v_pk_add_f32 v[132:133], v[132:133], v[164:165] neg_lo:[0,1] neg_hi:[0,1]
	v_add3_u32 v74, v74, v78, v79
	v_pk_mul_f32 v[164:165], v[132:133], s[4:5]
	v_xor_b32_e32 v78, 0x80000000, v75
	v_pk_fma_f32 v[132:133], v[132:133], s[12:13], v[164:165] op_sel:[0,0,1] op_sel_hi:[1,0,0]
	s_waitcnt lgkmcnt(0)
	v_pk_add_f32 v[164:165], v[134:135], v[166:167]
	v_pk_add_f32 v[134:135], v[134:135], v[166:167] neg_lo:[0,1] neg_hi:[0,1]
	v_mov_b32_e32 v79, v75
	v_pk_mul_f32 v[166:167], v[134:135], s[18:19]
	s_mov_b32 s50, s19
	v_pk_fma_f32 v[134:135], v[134:135], s[34:35], v[166:167] op_sel:[0,0,1] op_sel_hi:[1,0,0]
	v_pk_add_f32 v[166:167], v[168:169], v[150:151]
	v_pk_add_f32 v[150:151], v[168:169], v[150:151] neg_lo:[0,1] neg_hi:[0,1]
	v_pk_add_f32 v[168:169], v[136:137], v[120:121]
	v_pk_add_f32 v[120:121], v[136:137], v[120:121] neg_lo:[0,1] neg_hi:[0,1]
	s_mov_b32 s51, s18
	v_pk_mul_f32 v[136:137], v[120:121], s[4:5]
	s_mov_b32 s52, s23
	v_pk_fma_f32 v[120:121], v[120:121], s[6:7], v[136:137] op_sel:[0,0,1] op_sel_hi:[1,0,0]
	v_pk_add_f32 v[136:137], v[138:139], v[154:155]
	v_pk_add_f32 v[138:139], v[138:139], v[154:155] neg_lo:[0,1] neg_hi:[0,1]
	s_mov_b32 s53, s22
	v_pk_mul_f32 v[154:155], v[138:139], s[8:9]
	v_pk_fma_f32 v[138:139], v[138:139], s[10:11], v[154:155] op_sel:[0,0,1] op_sel_hi:[1,0,0]
	v_pk_add_f32 v[154:155], v[140:141], v[156:157]
	v_pk_add_f32 v[140:141], v[140:141], v[156:157] neg_lo:[0,1] neg_hi:[0,1]
	v_pk_mul_f32 v[156:157], v[140:141], s[12:13]
	v_pk_fma_f32 v[140:141], v[140:141], s[14:15], v[156:157] op_sel:[0,0,1] op_sel_hi:[1,0,0]
	v_pk_add_f32 v[156:157], v[142:143], v[158:159]
	v_pk_add_f32 v[158:159], v[142:143], v[158:159] op_sel:[1,1] op_sel_hi:[0,0] neg_lo:[0,1] neg_hi:[1,0]
	v_pk_add_f32 v[142:143], v[144:145], v[160:161]
	v_pk_add_f32 v[144:145], v[144:145], v[160:161] neg_lo:[0,1] neg_hi:[0,1]
	v_pk_mul_f32 v[160:161], v[144:145], s[12:13]
	v_pk_fma_f32 v[144:145], v[144:145], s[4:5], v[160:161] op_sel:[0,0,1] op_sel_hi:[1,0,0]
	v_pk_add_f32 v[160:161], v[146:147], v[162:163]
	v_pk_add_f32 v[146:147], v[146:147], v[162:163] neg_lo:[0,1] neg_hi:[0,1]
	v_pk_mul_f32 v[162:163], v[146:147], s[8:9]
	v_pk_fma_f32 v[146:147], v[146:147], s[8:9], v[162:163] op_sel:[0,0,1] op_sel_hi:[1,0,0]
	v_pk_add_f32 v[162:163], v[148:149], v[164:165]
	v_pk_add_f32 v[148:149], v[148:149], v[164:165] neg_lo:[0,1] neg_hi:[0,1]
	v_pk_mul_f32 v[164:165], v[148:149], s[4:5]
	v_pk_fma_f32 v[148:149], v[148:149], s[12:13], v[164:165] op_sel:[0,0,1] op_sel_hi:[1,0,0]
	v_pk_add_f32 v[164:165], v[66:67], v[152:153]
	v_pk_add_f32 v[66:67], v[66:67], v[152:153] neg_lo:[0,1] neg_hi:[0,1]
	v_pk_add_f32 v[152:153], v[68:69], v[122:123]
	v_pk_add_f32 v[68:69], v[68:69], v[122:123] neg_lo:[0,1] neg_hi:[0,1]
	v_pk_mul_f32 v[122:123], v[68:69], s[4:5]
	v_pk_fma_f32 v[68:69], v[68:69], s[6:7], v[122:123] op_sel:[0,0,1] op_sel_hi:[1,0,0]
	v_pk_add_f32 v[122:123], v[72:73], v[124:125]
	v_pk_add_f32 v[72:73], v[72:73], v[124:125] neg_lo:[0,1] neg_hi:[0,1]
	v_pk_mul_f32 v[124:125], v[72:73], s[8:9]
	v_pk_fma_f32 v[72:73], v[72:73], s[10:11], v[124:125] op_sel:[0,0,1] op_sel_hi:[1,0,0]
	v_pk_add_f32 v[124:125], v[76:77], v[126:127]
	v_pk_add_f32 v[76:77], v[76:77], v[126:127] neg_lo:[0,1] neg_hi:[0,1]
	v_pk_mul_f32 v[126:127], v[76:77], s[12:13]
	v_pk_fma_f32 v[76:77], v[76:77], s[14:15], v[126:127] op_sel:[0,0,1] op_sel_hi:[1,0,0]
	v_pk_add_f32 v[126:127], v[80:81], v[128:129]
	v_pk_add_f32 v[128:129], v[80:81], v[128:129] op_sel:[1,1] op_sel_hi:[0,0] neg_lo:[0,1] neg_hi:[1,0]
	v_pk_add_f32 v[80:81], v[82:83], v[130:131]
	v_pk_add_f32 v[82:83], v[82:83], v[130:131] neg_lo:[0,1] neg_hi:[0,1]
	v_pk_mul_f32 v[130:131], v[82:83], s[12:13]
	v_pk_fma_f32 v[82:83], v[82:83], s[4:5], v[130:131] op_sel:[0,0,1] op_sel_hi:[1,0,0]
	v_pk_add_f32 v[130:131], v[116:117], v[132:133]
	v_pk_add_f32 v[116:117], v[116:117], v[132:133] neg_lo:[0,1] neg_hi:[0,1]
	v_pk_mul_f32 v[132:133], v[116:117], s[8:9]
	v_pk_fma_f32 v[116:117], v[116:117], s[8:9], v[132:133] op_sel:[0,0,1] op_sel_hi:[1,0,0]
	v_pk_add_f32 v[132:133], v[118:119], v[134:135]
	v_pk_add_f32 v[118:119], v[118:119], v[134:135] neg_lo:[0,1] neg_hi:[0,1]
	v_pk_mul_f32 v[134:135], v[118:119], s[4:5]
	v_pk_fma_f32 v[118:119], v[118:119], s[12:13], v[134:135] op_sel:[0,0,1] op_sel_hi:[1,0,0]
	v_pk_add_f32 v[134:135], v[166:167], v[156:157]
	v_pk_add_f32 v[156:157], v[166:167], v[156:157] neg_lo:[0,1] neg_hi:[0,1]
	v_pk_add_f32 v[166:167], v[168:169], v[142:143]
	v_pk_add_f32 v[142:143], v[168:169], v[142:143] neg_lo:[0,1] neg_hi:[0,1]
	v_pk_mul_f32 v[168:169], v[142:143], s[8:9]
	v_pk_fma_f32 v[142:143], v[142:143], s[10:11], v[168:169] op_sel:[0,0,1] op_sel_hi:[1,0,0]
	v_pk_add_f32 v[168:169], v[136:137], v[160:161]
	v_pk_add_f32 v[160:161], v[136:137], v[160:161] op_sel:[1,1] op_sel_hi:[0,0] neg_lo:[0,1] neg_hi:[1,0]
	v_pk_add_f32 v[136:137], v[154:155], v[162:163]
	v_pk_add_f32 v[154:155], v[154:155], v[162:163] neg_lo:[0,1] neg_hi:[0,1]
	v_pk_mul_f32 v[162:163], v[154:155], s[8:9]
	v_pk_fma_f32 v[154:155], v[154:155], s[8:9], v[162:163] op_sel:[0,0,1] op_sel_hi:[1,0,0]
	v_pk_add_f32 v[162:163], v[150:151], v[158:159]
	v_pk_add_f32 v[150:151], v[150:151], v[158:159] neg_lo:[0,1] neg_hi:[0,1]
	v_pk_add_f32 v[158:159], v[120:121], v[144:145]
	v_pk_add_f32 v[120:121], v[120:121], v[144:145] neg_lo:[0,1] neg_hi:[0,1]
	v_pk_mul_f32 v[144:145], v[120:121], s[8:9]
	v_pk_fma_f32 v[120:121], v[120:121], s[10:11], v[144:145] op_sel:[0,0,1] op_sel_hi:[1,0,0]
	v_pk_add_f32 v[144:145], v[138:139], v[146:147]
	v_pk_add_f32 v[146:147], v[138:139], v[146:147] op_sel:[1,1] op_sel_hi:[0,0] neg_lo:[0,1] neg_hi:[1,0]
	v_pk_add_f32 v[138:139], v[140:141], v[148:149]
	v_pk_add_f32 v[140:141], v[140:141], v[148:149] neg_lo:[0,1] neg_hi:[0,1]
	v_pk_mul_f32 v[148:149], v[140:141], s[8:9]
	v_pk_fma_f32 v[140:141], v[140:141], s[8:9], v[148:149] op_sel:[0,0,1] op_sel_hi:[1,0,0]
	v_pk_add_f32 v[148:149], v[164:165], v[126:127]
	v_pk_add_f32 v[126:127], v[164:165], v[126:127] neg_lo:[0,1] neg_hi:[0,1]
	v_pk_add_f32 v[164:165], v[152:153], v[80:81]
	v_pk_add_f32 v[80:81], v[152:153], v[80:81] neg_lo:[0,1] neg_hi:[0,1]
	v_pk_mul_f32 v[152:153], v[80:81], s[8:9]
	v_pk_fma_f32 v[80:81], v[80:81], s[10:11], v[152:153] op_sel:[0,0,1] op_sel_hi:[1,0,0]
	v_pk_add_f32 v[152:153], v[122:123], v[130:131]
	v_pk_add_f32 v[130:131], v[122:123], v[130:131] op_sel:[1,1] op_sel_hi:[0,0] neg_lo:[0,1] neg_hi:[1,0]
	v_pk_add_f32 v[122:123], v[124:125], v[132:133]
	v_pk_add_f32 v[124:125], v[124:125], v[132:133] neg_lo:[0,1] neg_hi:[0,1]
	v_pk_mul_f32 v[132:133], v[124:125], s[8:9]
	v_pk_fma_f32 v[124:125], v[124:125], s[8:9], v[132:133] op_sel:[0,0,1] op_sel_hi:[1,0,0]
	v_pk_add_f32 v[132:133], v[66:67], v[128:129]
	v_pk_add_f32 v[66:67], v[66:67], v[128:129] neg_lo:[0,1] neg_hi:[0,1]
	v_pk_add_f32 v[128:129], v[68:69], v[82:83]
	v_pk_add_f32 v[68:69], v[68:69], v[82:83] neg_lo:[0,1] neg_hi:[0,1]
	v_pk_mul_f32 v[82:83], v[68:69], s[8:9]
	v_pk_fma_f32 v[68:69], v[68:69], s[10:11], v[82:83] op_sel:[0,0,1] op_sel_hi:[1,0,0]
	v_pk_add_f32 v[82:83], v[72:73], v[116:117]
	v_pk_add_f32 v[116:117], v[72:73], v[116:117] op_sel:[1,1] op_sel_hi:[0,0] neg_lo:[0,1] neg_hi:[1,0]
	v_pk_add_f32 v[72:73], v[76:77], v[118:119]
	v_pk_add_f32 v[76:77], v[76:77], v[118:119] neg_lo:[0,1] neg_hi:[0,1]
	v_pk_add_f32 v[174:175], v[66:67], v[116:117]
	v_pk_mul_f32 v[118:119], v[76:77], s[8:9]
	v_pk_add_f32 v[116:117], v[66:67], v[116:117] neg_lo:[0,1] neg_hi:[0,1]
	v_pk_fma_f32 v[76:77], v[76:77], s[8:9], v[118:119] op_sel:[0,0,1] op_sel_hi:[1,0,0]
	v_pk_add_f32 v[118:119], v[134:135], v[168:169]
	v_pk_add_f32 v[134:135], v[134:135], v[168:169] neg_lo:[0,1] neg_hi:[0,1]
	v_pk_add_f32 v[168:169], v[166:167], v[136:137]
	v_pk_add_f32 v[166:167], v[166:167], v[136:137] op_sel:[1,1] op_sel_hi:[0,0] neg_lo:[0,1] neg_hi:[1,0]
	v_pk_add_f32 v[180:181], v[118:119], v[168:169]
	v_pk_add_f32 v[136:137], v[156:157], v[160:161]
	v_pk_add_f32 v[156:157], v[156:157], v[160:161] neg_lo:[0,1] neg_hi:[0,1]
	v_pk_add_f32 v[160:161], v[142:143], v[154:155]
	v_pk_add_f32 v[154:155], v[142:143], v[154:155] op_sel:[1,1] op_sel_hi:[0,0] neg_lo:[0,1] neg_hi:[1,0]
	v_pk_add_f32 v[178:179], v[68:69], v[76:77] op_sel:[1,1] op_sel_hi:[0,0] neg_lo:[0,1] neg_hi:[1,0]
	v_pk_add_f32 v[142:143], v[162:163], v[144:145]
	v_pk_add_f32 v[144:145], v[162:163], v[144:145] neg_lo:[0,1] neg_hi:[0,1]
	v_pk_add_f32 v[162:163], v[158:159], v[138:139]
	v_pk_add_f32 v[158:159], v[158:159], v[138:139] op_sel:[1,1] op_sel_hi:[0,0] neg_lo:[0,1] neg_hi:[1,0]
	ds_write_b64 v74, v[180:181]
	v_pk_add_f32 v[138:139], v[150:151], v[146:147]
	v_pk_add_f32 v[146:147], v[150:151], v[146:147] neg_lo:[0,1] neg_hi:[0,1]
	v_pk_add_f32 v[150:151], v[120:121], v[140:141]
	v_pk_add_f32 v[140:141], v[120:121], v[140:141] op_sel:[1,1] op_sel_hi:[0,0] neg_lo:[0,1] neg_hi:[1,0]
	v_cos_f32_e32 v74, v115
	v_pk_add_f32 v[120:121], v[148:149], v[152:153]
	v_pk_add_f32 v[148:149], v[148:149], v[152:153] neg_lo:[0,1] neg_hi:[0,1]
	v_pk_add_f32 v[152:153], v[164:165], v[122:123]
	v_pk_add_f32 v[164:165], v[164:165], v[122:123] op_sel:[1,1] op_sel_hi:[0,0] neg_lo:[0,1] neg_hi:[1,0]
	v_pk_add_f32 v[122:123], v[126:127], v[130:131]
	v_pk_add_f32 v[126:127], v[126:127], v[130:131] neg_lo:[0,1] neg_hi:[0,1]
	v_pk_add_f32 v[130:131], v[80:81], v[124:125]
	v_pk_add_f32 v[124:125], v[80:81], v[124:125] op_sel:[1,1] op_sel_hi:[0,0] neg_lo:[0,1] neg_hi:[1,0]
	v_pk_add_f32 v[80:81], v[132:133], v[82:83]
	v_pk_add_f32 v[132:133], v[132:133], v[82:83] neg_lo:[0,1] neg_hi:[0,1]
	v_pk_add_f32 v[176:177], v[68:69], v[76:77]
	v_pk_add_f32 v[118:119], v[118:119], v[168:169] neg_lo:[0,1] neg_hi:[0,1]
	v_pk_add_f32 v[168:169], v[134:135], v[166:167]
	v_pk_add_f32 v[82:83], v[134:135], v[166:167] neg_lo:[0,1] neg_hi:[0,1]
	v_pk_add_f32 v[134:135], v[136:137], v[160:161]
	v_pk_add_f32 v[136:137], v[136:137], v[160:161] neg_lo:[0,1] neg_hi:[0,1]
	v_pk_add_f32 v[160:161], v[156:157], v[154:155]
	v_pk_add_f32 v[68:69], v[156:157], v[154:155] neg_lo:[0,1] neg_hi:[0,1]
	v_pk_add_f32 v[154:155], v[142:143], v[162:163]
	v_pk_add_f32 v[142:143], v[142:143], v[162:163] neg_lo:[0,1] neg_hi:[0,1]
	v_pk_add_f32 v[156:157], v[144:145], v[158:159]
	v_pk_add_f32 v[76:77], v[144:145], v[158:159] neg_lo:[0,1] neg_hi:[0,1]
	v_pk_add_f32 v[144:145], v[138:139], v[150:151]
	v_pk_add_f32 v[138:139], v[138:139], v[150:151] neg_lo:[0,1] neg_hi:[0,1]
	v_pk_add_f32 v[150:151], v[146:147], v[140:141]
	v_pk_add_f32 v[66:67], v[146:147], v[140:141] neg_lo:[0,1] neg_hi:[0,1]
	v_pk_add_f32 v[140:141], v[120:121], v[152:153]
	v_pk_add_f32 v[162:163], v[116:117], v[178:179]
	v_pk_add_f32 v[70:71], v[116:117], v[178:179] neg_lo:[0,1] neg_hi:[0,1]
	v_mov_b32_e32 v116, v75
	v_pk_mul_f32 v[116:117], v[116:117], v[140:141] op_sel:[0,1] op_sel_hi:[0,0] neg_hi:[1,0]
	v_pk_fma_f32 v[116:117], v[140:141], v[74:75], v[116:117] op_sel_hi:[1,0,1]
	ds_write_b64 v222, v[116:117] offset:256
	v_pk_mul_f32 v[114:115], v[78:79], v[74:75] op_sel:[0,1] op_sel_hi:[1,0]
	v_pk_add_f32 v[172:173], v[128:129], v[72:73]
	v_pk_fma_f32 v[114:115], v[74:75], v[74:75], v[114:115] op_sel_hi:[1,0,1]
	v_pk_add_f32 v[128:129], v[128:129], v[72:73] op_sel:[1,1] op_sel_hi:[0,0] neg_lo:[0,1] neg_hi:[1,0]
	v_pk_mul_f32 v[116:117], v[154:155], v[114:115] op_sel:[1,1] op_sel_hi:[0,1] neg_hi:[0,1]
	v_pk_fma_f32 v[116:117], v[154:155], v[114:115], v[116:117] op_sel_hi:[1,0,1]
	ds_write_b64 v222, v[116:117] offset:520
	v_pk_mul_f32 v[116:117], v[78:79], v[114:115] op_sel:[0,1] op_sel_hi:[1,0]
	v_pk_add_f32 v[120:121], v[120:121], v[152:153] neg_lo:[0,1] neg_hi:[0,1]
	v_pk_fma_f32 v[114:115], v[114:115], v[74:75], v[116:117] op_sel_hi:[1,0,1]
	v_pk_add_f32 v[152:153], v[122:123], v[130:131]
	v_pk_add_f32 v[122:123], v[122:123], v[130:131] neg_lo:[0,1] neg_hi:[0,1]
	v_pk_add_f32 v[130:131], v[126:127], v[124:125]
	v_pk_add_f32 v[72:73], v[126:127], v[124:125] neg_lo:[0,1] neg_hi:[0,1]
	v_pk_add_f32 v[124:125], v[80:81], v[172:173]
	v_pk_mul_f32 v[116:117], v[124:125], v[114:115] op_sel:[1,1] op_sel_hi:[0,1] neg_hi:[0,1]
	v_pk_add_f32 v[126:127], v[80:81], v[172:173] neg_lo:[0,1] neg_hi:[0,1]
	v_pk_fma_f32 v[116:117], v[124:125], v[114:115], v[116:117] op_sel_hi:[1,0,1]
	ds_write_b64 v222, v[116:117] offset:784
	v_pk_mul_f32 v[112:113], v[78:79], v[114:115] op_sel:[0,1] op_sel_hi:[1,0]
	v_pk_add_f32 v[158:159], v[132:133], v[128:129]
	v_pk_fma_f32 v[112:113], v[114:115], v[74:75], v[112:113] op_sel_hi:[1,0,1]
	v_pk_add_f32 v[80:81], v[132:133], v[128:129] neg_lo:[0,1] neg_hi:[0,1]
	v_pk_add_f32 v[128:129], v[174:175], v[176:177]
	v_pk_mul_f32 v[114:115], v[134:135], v[112:113] op_sel:[1,1] op_sel_hi:[0,1] neg_hi:[0,1]
	v_pk_add_f32 v[146:147], v[148:149], v[164:165]
	v_pk_fma_f32 v[114:115], v[134:135], v[112:113], v[114:115] op_sel_hi:[1,0,1]
	ds_write_b64 v222, v[114:115] offset:1048
	v_pk_mul_f32 v[114:115], v[78:79], v[112:113] op_sel:[0,1] op_sel_hi:[1,0]
	v_pk_add_f32 v[132:133], v[174:175], v[176:177] neg_lo:[0,1] neg_hi:[0,1]
	v_pk_fma_f32 v[112:113], v[112:113], v[74:75], v[114:115] op_sel_hi:[1,0,1]
	v_pk_add_f32 v[148:149], v[148:149], v[164:165] neg_lo:[0,1] neg_hi:[0,1]
	v_pk_mul_f32 v[114:115], v[152:153], v[112:113] op_sel:[1,1] op_sel_hi:[0,1] neg_hi:[0,1]
	v_pk_fma_f32 v[114:115], v[152:153], v[112:113], v[114:115] op_sel_hi:[1,0,1]
	ds_write_b64 v222, v[114:115] offset:1312
	v_pk_mul_f32 v[110:111], v[78:79], v[112:113] op_sel:[0,1] op_sel_hi:[1,0]
	v_pk_fma_f32 v[110:111], v[112:113], v[74:75], v[110:111] op_sel_hi:[1,0,1]
	v_pk_mul_f32 v[112:113], v[144:145], v[110:111] op_sel:[1,1] op_sel_hi:[0,1] neg_hi:[0,1]
	v_pk_fma_f32 v[112:113], v[144:145], v[110:111], v[112:113] op_sel_hi:[1,0,1]
	ds_write_b64 v222, v[112:113] offset:1576
	v_pk_mul_f32 v[112:113], v[78:79], v[110:111] op_sel:[0,1] op_sel_hi:[1,0]
	v_pk_fma_f32 v[110:111], v[110:111], v[74:75], v[112:113] op_sel_hi:[1,0,1]
	v_pk_mul_f32 v[112:113], v[128:129], v[110:111] op_sel:[1,1] op_sel_hi:[0,1] neg_hi:[0,1]
	v_pk_fma_f32 v[112:113], v[128:129], v[110:111], v[112:113] op_sel_hi:[1,0,1]
	ds_write_b64 v222, v[112:113] offset:1840
	v_pk_mul_f32 v[108:109], v[78:79], v[110:111] op_sel:[0,1] op_sel_hi:[1,0]
	v_pk_fma_f32 v[108:109], v[110:111], v[74:75], v[108:109] op_sel_hi:[1,0,1]
	v_pk_mul_f32 v[110:111], v[168:169], v[108:109] op_sel:[1,1] op_sel_hi:[0,1] neg_hi:[0,1]
	v_pk_fma_f32 v[110:111], v[168:169], v[108:109], v[110:111] op_sel_hi:[1,0,1]
	ds_write_b64 v222, v[110:111] offset:2104
	v_pk_mul_f32 v[110:111], v[78:79], v[108:109] op_sel:[0,1] op_sel_hi:[1,0]
	v_pk_fma_f32 v[108:109], v[108:109], v[74:75], v[110:111] op_sel_hi:[1,0,1]
	v_pk_mul_f32 v[110:111], v[146:147], v[108:109] op_sel:[1,1] op_sel_hi:[0,1] neg_hi:[0,1]
	v_pk_fma_f32 v[110:111], v[146:147], v[108:109], v[110:111] op_sel_hi:[1,0,1]
	ds_write_b64 v222, v[110:111] offset:2368
	v_pk_mul_f32 v[106:107], v[78:79], v[108:109] op_sel:[0,1] op_sel_hi:[1,0]
	v_pk_fma_f32 v[106:107], v[108:109], v[74:75], v[106:107] op_sel_hi:[1,0,1]
	v_pk_mul_f32 v[108:109], v[156:157], v[106:107] op_sel:[1,1] op_sel_hi:[0,1] neg_hi:[0,1]
	v_pk_fma_f32 v[108:109], v[156:157], v[106:107], v[108:109] op_sel_hi:[1,0,1]
	ds_write_b64 v222, v[108:109] offset:2632
	v_pk_mul_f32 v[108:109], v[78:79], v[106:107] op_sel:[0,1] op_sel_hi:[1,0]
	v_pk_fma_f32 v[106:107], v[106:107], v[74:75], v[108:109] op_sel_hi:[1,0,1]
	v_pk_mul_f32 v[108:109], v[158:159], v[106:107] op_sel:[1,1] op_sel_hi:[0,1] neg_hi:[0,1]
	v_pk_fma_f32 v[108:109], v[158:159], v[106:107], v[108:109] op_sel_hi:[1,0,1]
	ds_write_b64 v222, v[108:109] offset:2896
	v_pk_mul_f32 v[108:109], v[78:79], v[106:107] op_sel:[0,1] op_sel_hi:[1,0]
	v_pk_fma_f32 v[106:107], v[106:107], v[74:75], v[108:109] op_sel_hi:[1,0,1]
	v_pk_mul_f32 v[108:109], v[160:161], v[106:107] op_sel:[1,1] op_sel_hi:[0,1] neg_hi:[0,1]
	v_pk_fma_f32 v[108:109], v[160:161], v[106:107], v[108:109] op_sel_hi:[1,0,1]
	ds_write_b64 v222, v[108:109] offset:3160
	v_pk_mul_f32 v[102:103], v[78:79], v[106:107] op_sel:[0,1] op_sel_hi:[1,0]
	v_pk_fma_f32 v[102:103], v[106:107], v[74:75], v[102:103] op_sel_hi:[1,0,1]
	v_pk_mul_f32 v[106:107], v[130:131], v[102:103] op_sel:[1,1] op_sel_hi:[0,1] neg_hi:[0,1]
	v_pk_fma_f32 v[106:107], v[130:131], v[102:103], v[106:107] op_sel_hi:[1,0,1]
	ds_write_b64 v222, v[106:107] offset:3424
	v_pk_mul_f32 v[106:107], v[78:79], v[102:103] op_sel:[0,1] op_sel_hi:[1,0]
	v_pk_fma_f32 v[102:103], v[102:103], v[74:75], v[106:107] op_sel_hi:[1,0,1]
	v_pk_mul_f32 v[106:107], v[150:151], v[102:103] op_sel:[1,1] op_sel_hi:[0,1] neg_hi:[0,1]
	v_pk_fma_f32 v[106:107], v[150:151], v[102:103], v[106:107] op_sel_hi:[1,0,1]
	ds_write_b64 v222, v[106:107] offset:3688
	v_pk_mul_f32 v[100:101], v[78:79], v[102:103] op_sel:[0,1] op_sel_hi:[1,0]
	v_pk_fma_f32 v[100:101], v[102:103], v[74:75], v[100:101] op_sel_hi:[1,0,1]
	v_pk_mul_f32 v[102:103], v[162:163], v[100:101] op_sel:[1,1] op_sel_hi:[0,1] neg_hi:[0,1]
	v_pk_fma_f32 v[102:103], v[162:163], v[100:101], v[102:103] op_sel_hi:[1,0,1]
	ds_write_b64 v222, v[102:103] offset:3952
	v_pk_mul_f32 v[102:103], v[78:79], v[100:101] op_sel:[0,1] op_sel_hi:[1,0]
	v_pk_fma_f32 v[100:101], v[100:101], v[74:75], v[102:103] op_sel_hi:[1,0,1]
	v_pk_mul_f32 v[102:103], v[118:119], v[100:101] op_sel:[1,1] op_sel_hi:[0,1] neg_hi:[0,1]
	v_pk_fma_f32 v[102:103], v[118:119], v[100:101], v[102:103] op_sel_hi:[1,0,1]
	ds_write_b64 v222, v[102:103] offset:4216
	v_pk_mul_f32 v[98:99], v[78:79], v[100:101] op_sel:[0,1] op_sel_hi:[1,0]
	v_pk_fma_f32 v[98:99], v[100:101], v[74:75], v[98:99] op_sel_hi:[1,0,1]
	v_pk_mul_f32 v[100:101], v[120:121], v[98:99] op_sel:[1,1] op_sel_hi:[0,1] neg_hi:[0,1]
	v_pk_fma_f32 v[100:101], v[120:121], v[98:99], v[100:101] op_sel_hi:[1,0,1]
	ds_write_b64 v222, v[100:101] offset:4480
	v_pk_mul_f32 v[100:101], v[78:79], v[98:99] op_sel:[0,1] op_sel_hi:[1,0]
	v_pk_fma_f32 v[98:99], v[98:99], v[74:75], v[100:101] op_sel_hi:[1,0,1]
	v_pk_mul_f32 v[100:101], v[142:143], v[98:99] op_sel:[1,1] op_sel_hi:[0,1] neg_hi:[0,1]
	v_pk_fma_f32 v[100:101], v[142:143], v[98:99], v[100:101] op_sel_hi:[1,0,1]
	ds_write_b64 v222, v[100:101] offset:4744
	v_pk_mul_f32 v[96:97], v[78:79], v[98:99] op_sel:[0,1] op_sel_hi:[1,0]
	v_pk_fma_f32 v[96:97], v[98:99], v[74:75], v[96:97] op_sel_hi:[1,0,1]
	v_pk_mul_f32 v[98:99], v[126:127], v[96:97] op_sel:[1,1] op_sel_hi:[0,1] neg_hi:[0,1]
	v_pk_fma_f32 v[98:99], v[126:127], v[96:97], v[98:99] op_sel_hi:[1,0,1]
	ds_write_b64 v222, v[98:99] offset:5008
	v_pk_mul_f32 v[98:99], v[78:79], v[96:97] op_sel:[0,1] op_sel_hi:[1,0]
	v_pk_fma_f32 v[96:97], v[96:97], v[74:75], v[98:99] op_sel_hi:[1,0,1]
	v_pk_mul_f32 v[98:99], v[136:137], v[96:97] op_sel:[1,1] op_sel_hi:[0,1] neg_hi:[0,1]
	v_pk_fma_f32 v[98:99], v[136:137], v[96:97], v[98:99] op_sel_hi:[1,0,1]
	ds_write_b64 v222, v[98:99] offset:5272
	v_pk_mul_f32 v[94:95], v[78:79], v[96:97] op_sel:[0,1] op_sel_hi:[1,0]
	v_pk_fma_f32 v[94:95], v[96:97], v[74:75], v[94:95] op_sel_hi:[1,0,1]
	v_pk_mul_f32 v[96:97], v[122:123], v[94:95] op_sel:[1,1] op_sel_hi:[0,1] neg_hi:[0,1]
	v_pk_fma_f32 v[96:97], v[122:123], v[94:95], v[96:97] op_sel_hi:[1,0,1]
	ds_write_b64 v222, v[96:97] offset:5536
	v_pk_mul_f32 v[96:97], v[78:79], v[94:95] op_sel:[0,1] op_sel_hi:[1,0]
	v_pk_fma_f32 v[94:95], v[94:95], v[74:75], v[96:97] op_sel_hi:[1,0,1]
	v_pk_mul_f32 v[96:97], v[138:139], v[94:95] op_sel:[1,1] op_sel_hi:[0,1] neg_hi:[0,1]
	v_pk_fma_f32 v[96:97], v[138:139], v[94:95], v[96:97] op_sel_hi:[1,0,1]
	ds_write_b64 v222, v[96:97] offset:5800
	v_pk_mul_f32 v[92:93], v[78:79], v[94:95] op_sel:[0,1] op_sel_hi:[1,0]
	v_pk_fma_f32 v[92:93], v[94:95], v[74:75], v[92:93] op_sel_hi:[1,0,1]
	v_pk_mul_f32 v[94:95], v[132:133], v[92:93] op_sel:[1,1] op_sel_hi:[0,1] neg_hi:[0,1]
	v_pk_fma_f32 v[94:95], v[132:133], v[92:93], v[94:95] op_sel_hi:[1,0,1]
	ds_write_b64 v222, v[94:95] offset:6064
	v_pk_mul_f32 v[94:95], v[78:79], v[92:93] op_sel:[0,1] op_sel_hi:[1,0]
	v_pk_fma_f32 v[92:93], v[92:93], v[74:75], v[94:95] op_sel_hi:[1,0,1]
	v_pk_mul_f32 v[94:95], v[82:83], v[92:93] op_sel:[1,1] op_sel_hi:[0,1] neg_hi:[0,1]
	v_pk_fma_f32 v[82:83], v[82:83], v[92:93], v[94:95] op_sel_hi:[1,0,1]
	ds_write_b64 v222, v[82:83] offset:6328
	v_pk_mul_f32 v[82:83], v[78:79], v[92:93] op_sel:[0,1] op_sel_hi:[1,0]
	v_pk_fma_f32 v[82:83], v[92:93], v[74:75], v[82:83] op_sel_hi:[1,0,1]
	v_pk_mul_f32 v[90:91], v[148:149], v[82:83] op_sel:[1,1] op_sel_hi:[0,1] neg_hi:[0,1]
	v_pk_fma_f32 v[90:91], v[148:149], v[82:83], v[90:91] op_sel_hi:[1,0,1]
	ds_write_b64 v222, v[90:91] offset:6592
	v_pk_mul_f32 v[90:91], v[78:79], v[82:83] op_sel:[0,1] op_sel_hi:[1,0]
	v_pk_fma_f32 v[82:83], v[82:83], v[74:75], v[90:91] op_sel_hi:[1,0,1]
	v_pk_mul_f32 v[90:91], v[76:77], v[82:83] op_sel:[1,1] op_sel_hi:[0,1] neg_hi:[0,1]
	v_pk_fma_f32 v[76:77], v[76:77], v[82:83], v[90:91] op_sel_hi:[1,0,1]
	ds_write_b64 v222, v[76:77] offset:6856
	v_pk_mul_f32 v[76:77], v[78:79], v[82:83] op_sel:[0,1] op_sel_hi:[1,0]
	v_pk_fma_f32 v[76:77], v[82:83], v[74:75], v[76:77] op_sel_hi:[1,0,1]
	v_pk_mul_f32 v[82:83], v[80:81], v[76:77] op_sel:[1,1] op_sel_hi:[0,1] neg_hi:[0,1]
	v_pk_fma_f32 v[80:81], v[80:81], v[76:77], v[82:83] op_sel_hi:[1,0,1]
	ds_write_b64 v222, v[80:81] offset:7120
	v_pk_mul_f32 v[80:81], v[78:79], v[76:77] op_sel:[0,1] op_sel_hi:[1,0]
	v_pk_fma_f32 v[76:77], v[76:77], v[74:75], v[80:81] op_sel_hi:[1,0,1]
	v_pk_mul_f32 v[80:81], v[68:69], v[76:77] op_sel:[1,1] op_sel_hi:[0,1] neg_hi:[0,1]
	v_pk_fma_f32 v[68:69], v[68:69], v[76:77], v[80:81] op_sel_hi:[1,0,1]
	ds_write_b64 v222, v[68:69] offset:7384
	v_pk_mul_f32 v[68:69], v[78:79], v[76:77] op_sel:[0,1] op_sel_hi:[1,0]
	v_pk_fma_f32 v[68:69], v[76:77], v[74:75], v[68:69] op_sel_hi:[1,0,1]
	v_pk_mul_f32 v[76:77], v[72:73], v[68:69] op_sel:[1,1] op_sel_hi:[0,1] neg_hi:[0,1]
	v_pk_fma_f32 v[72:73], v[72:73], v[68:69], v[76:77] op_sel_hi:[1,0,1]
	ds_write_b64 v222, v[72:73] offset:7648
	v_pk_mul_f32 v[72:73], v[78:79], v[68:69] op_sel:[0,1] op_sel_hi:[1,0]
	v_pk_fma_f32 v[68:69], v[68:69], v[74:75], v[72:73] op_sel_hi:[1,0,1]
	v_pk_mul_f32 v[72:73], v[66:67], v[68:69] op_sel:[1,1] op_sel_hi:[0,1] neg_hi:[0,1]
	v_pk_fma_f32 v[66:67], v[66:67], v[68:69], v[72:73] op_sel_hi:[1,0,1]
	ds_write_b64 v222, v[66:67] offset:7912
	v_pk_mul_f32 v[66:67], v[78:79], v[68:69] op_sel:[0,1] op_sel_hi:[1,0]
	v_pk_fma_f32 v[66:67], v[68:69], v[74:75], v[66:67] op_sel_hi:[1,0,1]
	v_pk_mul_f32 v[68:69], v[70:71], v[66:67] op_sel:[1,1] op_sel_hi:[0,1] neg_hi:[0,1]
	v_pk_fma_f32 v[66:67], v[70:71], v[66:67], v[68:69] op_sel_hi:[1,0,1]
	ds_write_b64 v222, v[66:67] offset:8176
	s_waitcnt lgkmcnt(0)
	s_barrier
	ds_read2_b64 v[66:69], v104 offset1:1
	ds_read2_b64 v[70:73], v104 offset0:2 offset1:3
	ds_read2_b64 v[74:77], v104 offset0:4 offset1:5
	ds_read2_b64 v[78:81], v104 offset0:6 offset1:7
	ds_read2_b64 v[82:85], v104 offset0:8 offset1:9
	ds_read2_b64 v[86:89], v104 offset0:10 offset1:11
	ds_read2_b64 v[90:93], v104 offset0:12 offset1:13
	ds_read2_b64 v[94:97], v104 offset0:14 offset1:15
	ds_read2_b64 v[98:101], v104 offset0:16 offset1:17
	ds_read2_b64 v[106:109], v104 offset0:18 offset1:19
	ds_read2_b64 v[110:113], v104 offset0:20 offset1:21
	ds_read2_b64 v[114:117], v104 offset0:22 offset1:23
	ds_read2_b64 v[118:121], v104 offset0:24 offset1:25
	ds_read2_b64 v[122:125], v104 offset0:26 offset1:27
	ds_read2_b64 v[126:129], v104 offset0:28 offset1:29
	ds_read2_b64 v[130:133], v104 offset0:30 offset1:31
	s_waitcnt lgkmcnt(7)
	v_pk_add_f32 v[102:103], v[66:67], v[98:99]
	v_pk_add_f32 v[66:67], v[66:67], v[98:99] neg_lo:[0,1] neg_hi:[0,1]
	v_pk_add_f32 v[98:99], v[68:69], v[100:101]
	v_pk_add_f32 v[68:69], v[68:69], v[100:101] neg_lo:[0,1] neg_hi:[0,1]
	global_load_dwordx2 v[134:135], v[2:3], off
	global_load_dwordx2 v[136:137], v[4:5], off
	global_load_dwordx2 v[138:139], v[6:7], off
	v_pk_mul_f32 v[100:101], v[68:69], s[18:19]
	global_load_dwordx2 v[148:149], v[14:15], off
	global_load_dwordx2 v[154:155], v[16:17], off
	v_pk_fma_f32 v[68:69], v[68:69], s[20:21], v[100:101] op_sel:[0,0,1] op_sel_hi:[1,0,0]
	s_waitcnt lgkmcnt(6)
	v_pk_add_f32 v[100:101], v[70:71], v[106:107]
	v_pk_add_f32 v[70:71], v[70:71], v[106:107] neg_lo:[0,1] neg_hi:[0,1]
	global_load_dwordx2 v[158:159], v[18:19], off
	v_pk_mul_f32 v[106:107], v[70:71], s[4:5]
	global_load_dwordx2 v[160:161], v[28:29], off
	global_load_dwordx2 v[164:165], v[32:33], off
	v_pk_fma_f32 v[70:71], v[70:71], s[6:7], v[106:107] op_sel:[0,0,1] op_sel_hi:[1,0,0]
	v_pk_add_f32 v[106:107], v[72:73], v[108:109]
	v_pk_add_f32 v[72:73], v[72:73], v[108:109] neg_lo:[0,1] neg_hi:[0,1]
	global_load_dwordx2 v[168:169], v[36:37], off
	v_pk_mul_f32 v[108:109], v[72:73], s[22:23]
	global_load_dwordx2 v[172:173], v[44:45], off
	v_pk_fma_f32 v[72:73], v[72:73], s[24:25], v[108:109] op_sel:[0,0,1] op_sel_hi:[1,0,0]
	s_waitcnt lgkmcnt(5)
	v_pk_add_f32 v[108:109], v[74:75], v[110:111]
	v_pk_add_f32 v[74:75], v[74:75], v[110:111] neg_lo:[0,1] neg_hi:[0,1]
	global_load_dwordx2 v[174:175], v[52:53], off
	v_pk_mul_f32 v[110:111], v[74:75], s[8:9]
	global_load_dwordx2 v[176:177], v[60:61], off
	v_pk_fma_f32 v[74:75], v[74:75], s[10:11], v[110:111] op_sel:[0,0,1] op_sel_hi:[1,0,0]
	v_pk_add_f32 v[110:111], v[76:77], v[112:113]
	v_pk_add_f32 v[76:77], v[76:77], v[112:113] neg_lo:[0,1] neg_hi:[0,1]
	v_pk_mul_f32 v[112:113], v[76:77], s[26:27]
	v_pk_fma_f32 v[76:77], v[76:77], s[0:1], v[112:113] op_sel:[0,0,1] op_sel_hi:[1,0,0]
	s_waitcnt lgkmcnt(4)
	v_pk_add_f32 v[112:113], v[78:79], v[114:115]
	v_pk_add_f32 v[78:79], v[78:79], v[114:115] neg_lo:[0,1] neg_hi:[0,1]
	v_pk_mul_f32 v[114:115], v[78:79], s[12:13]
	v_pk_fma_f32 v[78:79], v[78:79], s[14:15], v[114:115] op_sel:[0,0,1] op_sel_hi:[1,0,0]
	v_pk_add_f32 v[114:115], v[80:81], v[116:117]
	v_pk_add_f32 v[80:81], v[80:81], v[116:117] neg_lo:[0,1] neg_hi:[0,1]
	v_pk_mul_f32 v[116:117], v[80:81], s[34:35]
	v_pk_fma_f32 v[80:81], v[80:81], s[48:49], v[116:117] op_sel:[0,0,1] op_sel_hi:[1,0,0]
	s_waitcnt lgkmcnt(3)
	v_pk_add_f32 v[116:117], v[82:83], v[118:119]
	v_pk_add_f32 v[118:119], v[82:83], v[118:119] op_sel:[1,1] op_sel_hi:[0,0] neg_lo:[0,1] neg_hi:[1,0]
	v_pk_add_f32 v[82:83], v[84:85], v[120:121]
	v_pk_add_f32 v[84:85], v[84:85], v[120:121] neg_lo:[0,1] neg_hi:[0,1]
	v_pk_mul_f32 v[120:121], v[84:85], s[34:35]
	v_pk_fma_f32 v[84:85], v[84:85], s[18:19], v[120:121] op_sel:[0,0,1] op_sel_hi:[1,0,0]
	s_waitcnt lgkmcnt(2)
	v_pk_add_f32 v[120:121], v[86:87], v[122:123]
	v_pk_add_f32 v[86:87], v[86:87], v[122:123] neg_lo:[0,1] neg_hi:[0,1]
	v_pk_mul_f32 v[122:123], v[86:87], s[12:13]
	v_pk_fma_f32 v[86:87], v[86:87], s[4:5], v[122:123] op_sel:[0,0,1] op_sel_hi:[1,0,0]
	v_pk_add_f32 v[122:123], v[88:89], v[124:125]
	v_pk_add_f32 v[88:89], v[88:89], v[124:125] neg_lo:[0,1] neg_hi:[0,1]
	v_pk_mul_f32 v[124:125], v[88:89], s[26:27]
	v_pk_fma_f32 v[88:89], v[88:89], s[22:23], v[124:125] op_sel:[0,0,1] op_sel_hi:[1,0,0]
	s_waitcnt lgkmcnt(1)
	v_pk_add_f32 v[124:125], v[90:91], v[126:127]
	v_pk_add_f32 v[90:91], v[90:91], v[126:127] neg_lo:[0,1] neg_hi:[0,1]
	v_pk_mul_f32 v[126:127], v[90:91], s[8:9]
	v_pk_fma_f32 v[90:91], v[90:91], s[8:9], v[126:127] op_sel:[0,0,1] op_sel_hi:[1,0,0]
	v_pk_add_f32 v[126:127], v[92:93], v[128:129]
	v_pk_add_f32 v[92:93], v[92:93], v[128:129] neg_lo:[0,1] neg_hi:[0,1]
	v_pk_mul_f32 v[128:129], v[92:93], s[22:23]
	v_pk_fma_f32 v[92:93], v[92:93], s[26:27], v[128:129] op_sel:[0,0,1] op_sel_hi:[1,0,0]
	s_waitcnt lgkmcnt(0)
	v_pk_add_f32 v[128:129], v[94:95], v[130:131]
	v_pk_add_f32 v[94:95], v[94:95], v[130:131] neg_lo:[0,1] neg_hi:[0,1]
	v_pk_mul_f32 v[130:131], v[94:95], s[4:5]
	v_pk_fma_f32 v[94:95], v[94:95], s[12:13], v[130:131] op_sel:[0,0,1] op_sel_hi:[1,0,0]
	v_pk_add_f32 v[130:131], v[96:97], v[132:133]
	v_pk_add_f32 v[96:97], v[96:97], v[132:133] neg_lo:[0,1] neg_hi:[0,1]
	v_pk_mul_f32 v[132:133], v[96:97], s[18:19]
	v_pk_fma_f32 v[96:97], v[96:97], s[34:35], v[132:133] op_sel:[0,0,1] op_sel_hi:[1,0,0]
	v_pk_add_f32 v[132:133], v[102:103], v[116:117]
	v_pk_add_f32 v[102:103], v[102:103], v[116:117] neg_lo:[0,1] neg_hi:[0,1]
	v_pk_add_f32 v[116:117], v[98:99], v[82:83]
	v_pk_add_f32 v[82:83], v[98:99], v[82:83] neg_lo:[0,1] neg_hi:[0,1]
	v_pk_mul_f32 v[98:99], v[82:83], s[4:5]
	v_pk_fma_f32 v[82:83], v[82:83], s[6:7], v[98:99] op_sel:[0,0,1] op_sel_hi:[1,0,0]
	v_pk_add_f32 v[98:99], v[100:101], v[120:121]
	v_pk_add_f32 v[100:101], v[100:101], v[120:121] neg_lo:[0,1] neg_hi:[0,1]
	v_pk_mul_f32 v[120:121], v[100:101], s[8:9]
	v_pk_fma_f32 v[100:101], v[100:101], s[10:11], v[120:121] op_sel:[0,0,1] op_sel_hi:[1,0,0]
	v_pk_add_f32 v[120:121], v[106:107], v[122:123]
	v_pk_add_f32 v[106:107], v[106:107], v[122:123] neg_lo:[0,1] neg_hi:[0,1]
	v_pk_mul_f32 v[122:123], v[106:107], s[12:13]
	v_pk_fma_f32 v[106:107], v[106:107], s[14:15], v[122:123] op_sel:[0,0,1] op_sel_hi:[1,0,0]
	v_pk_add_f32 v[122:123], v[108:109], v[124:125]
	v_pk_add_f32 v[124:125], v[108:109], v[124:125] op_sel:[1,1] op_sel_hi:[0,0] neg_lo:[0,1] neg_hi:[1,0]
	v_pk_add_f32 v[108:109], v[110:111], v[126:127]
	v_pk_add_f32 v[110:111], v[110:111], v[126:127] neg_lo:[0,1] neg_hi:[0,1]
	v_pk_mul_f32 v[126:127], v[110:111], s[12:13]
	v_pk_fma_f32 v[110:111], v[110:111], s[4:5], v[126:127] op_sel:[0,0,1] op_sel_hi:[1,0,0]
	v_pk_add_f32 v[126:127], v[112:113], v[128:129]
	v_pk_add_f32 v[112:113], v[112:113], v[128:129] neg_lo:[0,1] neg_hi:[0,1]
	v_pk_mul_f32 v[128:129], v[112:113], s[8:9]
	v_pk_fma_f32 v[112:113], v[112:113], s[8:9], v[128:129] op_sel:[0,0,1] op_sel_hi:[1,0,0]
	v_pk_add_f32 v[128:129], v[114:115], v[130:131]
	v_pk_add_f32 v[114:115], v[114:115], v[130:131] neg_lo:[0,1] neg_hi:[0,1]
	v_pk_mul_f32 v[130:131], v[114:115], s[4:5]
	v_pk_fma_f32 v[114:115], v[114:115], s[12:13], v[130:131] op_sel:[0,0,1] op_sel_hi:[1,0,0]
	v_pk_add_f32 v[130:131], v[66:67], v[118:119]
	v_pk_add_f32 v[66:67], v[66:67], v[118:119] neg_lo:[0,1] neg_hi:[0,1]
	v_pk_add_f32 v[118:119], v[68:69], v[84:85]
	v_pk_add_f32 v[68:69], v[68:69], v[84:85] neg_lo:[0,1] neg_hi:[0,1]
	v_pk_mul_f32 v[84:85], v[68:69], s[4:5]
	v_pk_fma_f32 v[68:69], v[68:69], s[6:7], v[84:85] op_sel:[0,0,1] op_sel_hi:[1,0,0]
	v_pk_add_f32 v[84:85], v[70:71], v[86:87]
	v_pk_add_f32 v[70:71], v[70:71], v[86:87] neg_lo:[0,1] neg_hi:[0,1]
	v_pk_mul_f32 v[86:87], v[70:71], s[8:9]
	v_pk_fma_f32 v[70:71], v[70:71], s[10:11], v[86:87] op_sel:[0,0,1] op_sel_hi:[1,0,0]
	v_pk_add_f32 v[86:87], v[72:73], v[88:89]
	v_pk_add_f32 v[72:73], v[72:73], v[88:89] neg_lo:[0,1] neg_hi:[0,1]
	v_pk_mul_f32 v[88:89], v[72:73], s[12:13]
	v_pk_fma_f32 v[72:73], v[72:73], s[14:15], v[88:89] op_sel:[0,0,1] op_sel_hi:[1,0,0]
	v_pk_add_f32 v[88:89], v[74:75], v[90:91]
	v_pk_add_f32 v[90:91], v[74:75], v[90:91] op_sel:[1,1] op_sel_hi:[0,0] neg_lo:[0,1] neg_hi:[1,0]
	s_mov_b32 s15, s4
	v_pk_add_f32 v[74:75], v[76:77], v[92:93]
	v_pk_add_f32 v[76:77], v[76:77], v[92:93] neg_lo:[0,1] neg_hi:[0,1]
	v_pk_mul_f32 v[92:93], v[76:77], s[12:13]
	v_pk_fma_f32 v[76:77], v[76:77], s[4:5], v[92:93] op_sel:[0,0,1] op_sel_hi:[1,0,0]
	v_pk_add_f32 v[92:93], v[78:79], v[94:95]
	v_pk_add_f32 v[78:79], v[78:79], v[94:95] neg_lo:[0,1] neg_hi:[0,1]
	v_pk_mul_f32 v[94:95], v[78:79], s[8:9]
	v_pk_fma_f32 v[78:79], v[78:79], s[8:9], v[94:95] op_sel:[0,0,1] op_sel_hi:[1,0,0]
	v_pk_add_f32 v[94:95], v[80:81], v[96:97]
	v_pk_add_f32 v[80:81], v[80:81], v[96:97] neg_lo:[0,1] neg_hi:[0,1]
	v_pk_mul_f32 v[96:97], v[80:81], s[4:5]
	v_pk_fma_f32 v[80:81], v[80:81], s[12:13], v[96:97] op_sel:[0,0,1] op_sel_hi:[1,0,0]
	v_pk_add_f32 v[96:97], v[132:133], v[122:123]
	v_pk_add_f32 v[122:123], v[132:133], v[122:123] neg_lo:[0,1] neg_hi:[0,1]
	v_pk_add_f32 v[132:133], v[116:117], v[108:109]
	v_pk_add_f32 v[108:109], v[116:117], v[108:109] neg_lo:[0,1] neg_hi:[0,1]
	v_pk_mul_f32 v[116:117], v[108:109], s[8:9]
	v_pk_fma_f32 v[108:109], v[108:109], s[10:11], v[116:117] op_sel:[0,0,1] op_sel_hi:[1,0,0]
	v_pk_add_f32 v[116:117], v[98:99], v[126:127]
	v_pk_add_f32 v[126:127], v[98:99], v[126:127] op_sel:[1,1] op_sel_hi:[0,0] neg_lo:[0,1] neg_hi:[1,0]
	v_pk_add_f32 v[98:99], v[120:121], v[128:129]
	v_pk_add_f32 v[120:121], v[120:121], v[128:129] neg_lo:[0,1] neg_hi:[0,1]
	v_pk_mul_f32 v[128:129], v[120:121], s[8:9]
	v_pk_fma_f32 v[120:121], v[120:121], s[8:9], v[128:129] op_sel:[0,0,1] op_sel_hi:[1,0,0]
	v_pk_add_f32 v[128:129], v[102:103], v[124:125]
	v_pk_add_f32 v[102:103], v[102:103], v[124:125] neg_lo:[0,1] neg_hi:[0,1]
	v_pk_add_f32 v[124:125], v[82:83], v[110:111]
	v_pk_add_f32 v[82:83], v[82:83], v[110:111] neg_lo:[0,1] neg_hi:[0,1]
	v_pk_mul_f32 v[110:111], v[82:83], s[8:9]
	v_pk_fma_f32 v[82:83], v[82:83], s[10:11], v[110:111] op_sel:[0,0,1] op_sel_hi:[1,0,0]
	v_pk_add_f32 v[110:111], v[100:101], v[112:113]
	v_pk_add_f32 v[112:113], v[100:101], v[112:113] op_sel:[1,1] op_sel_hi:[0,0] neg_lo:[0,1] neg_hi:[1,0]
	v_pk_add_f32 v[100:101], v[106:107], v[114:115]
	v_pk_add_f32 v[106:107], v[106:107], v[114:115] neg_lo:[0,1] neg_hi:[0,1]
	v_pk_mul_f32 v[114:115], v[106:107], s[8:9]
	v_pk_fma_f32 v[106:107], v[106:107], s[8:9], v[114:115] op_sel:[0,0,1] op_sel_hi:[1,0,0]
	v_pk_add_f32 v[114:115], v[130:131], v[88:89]
	v_pk_add_f32 v[88:89], v[130:131], v[88:89] neg_lo:[0,1] neg_hi:[0,1]
	v_pk_add_f32 v[130:131], v[118:119], v[74:75]
	v_pk_add_f32 v[74:75], v[118:119], v[74:75] neg_lo:[0,1] neg_hi:[0,1]
	v_pk_mul_f32 v[118:119], v[74:75], s[8:9]
	v_pk_fma_f32 v[74:75], v[74:75], s[10:11], v[118:119] op_sel:[0,0,1] op_sel_hi:[1,0,0]
	v_pk_add_f32 v[118:119], v[84:85], v[92:93]
	v_pk_add_f32 v[92:93], v[84:85], v[92:93] op_sel:[1,1] op_sel_hi:[0,0] neg_lo:[0,1] neg_hi:[1,0]
	v_pk_add_f32 v[84:85], v[86:87], v[94:95]
	v_pk_add_f32 v[86:87], v[86:87], v[94:95] neg_lo:[0,1] neg_hi:[0,1]
	v_pk_add_f32 v[140:141], v[88:89], v[92:93]
	v_pk_mul_f32 v[94:95], v[86:87], s[8:9]
	v_pk_add_f32 v[88:89], v[88:89], v[92:93] neg_lo:[0,1] neg_hi:[0,1]
	v_pk_fma_f32 v[86:87], v[86:87], s[8:9], v[94:95] op_sel:[0,0,1] op_sel_hi:[1,0,0]
	v_pk_add_f32 v[94:95], v[66:67], v[90:91]
	v_pk_add_f32 v[66:67], v[66:67], v[90:91] neg_lo:[0,1] neg_hi:[0,1]
	v_pk_add_f32 v[90:91], v[68:69], v[76:77]
	v_pk_add_f32 v[68:69], v[68:69], v[76:77] neg_lo:[0,1] neg_hi:[0,1]
	v_pk_add_f32 v[92:93], v[74:75], v[86:87]
	v_pk_mul_f32 v[76:77], v[68:69], s[8:9]
	v_pk_add_f32 v[142:143], v[74:75], v[86:87] op_sel:[1,1] op_sel_hi:[0,0] neg_lo:[0,1] neg_hi:[1,0]
	v_pk_fma_f32 v[68:69], v[68:69], s[10:11], v[76:77] op_sel:[0,0,1] op_sel_hi:[1,0,0]
	v_pk_add_f32 v[76:77], v[70:71], v[78:79]
	v_pk_add_f32 v[78:79], v[70:71], v[78:79] op_sel:[1,1] op_sel_hi:[0,0] neg_lo:[0,1] neg_hi:[1,0]
	global_load_dwordx2 v[86:87], v[10:11], off
	v_pk_add_f32 v[70:71], v[72:73], v[80:81]
	v_pk_add_f32 v[72:73], v[72:73], v[80:81] neg_lo:[0,1] neg_hi:[0,1]
	v_pk_mul_f32 v[80:81], v[72:73], s[8:9]
	v_pk_fma_f32 v[72:73], v[72:73], s[8:9], v[80:81] op_sel:[0,0,1] op_sel_hi:[1,0,0]
	v_pk_add_f32 v[80:81], v[96:97], v[116:117]
	v_pk_add_f32 v[96:97], v[96:97], v[116:117] neg_lo:[0,1] neg_hi:[0,1]
	v_pk_add_f32 v[116:117], v[132:133], v[98:99]
	v_pk_add_f32 v[132:133], v[132:133], v[98:99] op_sel:[1,1] op_sel_hi:[0,0] neg_lo:[0,1] neg_hi:[1,0]
	v_pk_add_f32 v[74:75], v[94:95], v[76:77]
	v_pk_add_f32 v[98:99], v[122:123], v[126:127]
	v_pk_add_f32 v[122:123], v[122:123], v[126:127] neg_lo:[0,1] neg_hi:[0,1]
	v_pk_add_f32 v[126:127], v[108:109], v[120:121]
	v_pk_add_f32 v[120:121], v[108:109], v[120:121] op_sel:[1,1] op_sel_hi:[0,0] neg_lo:[0,1] neg_hi:[1,0]
	v_pk_add_f32 v[76:77], v[94:95], v[76:77] neg_lo:[0,1] neg_hi:[0,1]
	v_pk_add_f32 v[108:109], v[128:129], v[110:111]
	v_pk_add_f32 v[110:111], v[128:129], v[110:111] neg_lo:[0,1] neg_hi:[0,1]
	v_pk_add_f32 v[128:129], v[124:125], v[100:101]
	v_pk_add_f32 v[124:125], v[124:125], v[100:101] op_sel:[1,1] op_sel_hi:[0,0] neg_lo:[0,1] neg_hi:[1,0]
	global_load_dwordx2 v[94:95], v[12:13], off
	v_pk_add_f32 v[100:101], v[102:103], v[112:113]
	v_pk_add_f32 v[102:103], v[102:103], v[112:113] neg_lo:[0,1] neg_hi:[0,1]
	v_pk_add_f32 v[112:113], v[82:83], v[106:107]
	v_pk_add_f32 v[106:107], v[82:83], v[106:107] op_sel:[1,1] op_sel_hi:[0,0] neg_lo:[0,1] neg_hi:[1,0]
	v_pk_add_f32 v[146:147], v[66:67], v[78:79]
	v_pk_add_f32 v[82:83], v[114:115], v[118:119]
	v_pk_add_f32 v[114:115], v[114:115], v[118:119] neg_lo:[0,1] neg_hi:[0,1]
	v_pk_add_f32 v[118:119], v[130:131], v[84:85]
	v_pk_add_f32 v[130:131], v[130:131], v[84:85] op_sel:[1,1] op_sel_hi:[0,0] neg_lo:[0,1] neg_hi:[1,0]
	v_pk_add_f32 v[78:79], v[66:67], v[78:79] neg_lo:[0,1] neg_hi:[0,1]
	global_load_dwordx2 v[84:85], v[8:9], off
	v_pk_add_f32 v[152:153], v[68:69], v[72:73] op_sel:[1,1] op_sel_hi:[0,0] neg_lo:[0,1] neg_hi:[1,0]
	v_pk_add_f32 v[150:151], v[68:69], v[72:73]
	v_pk_add_f32 v[156:157], v[80:81], v[116:117]
	v_pk_add_f32 v[80:81], v[80:81], v[116:117] neg_lo:[0,1] neg_hi:[0,1]
	v_pk_add_f32 v[116:117], v[96:97], v[132:133]
	v_pk_add_f32 v[68:69], v[96:97], v[132:133] neg_lo:[0,1] neg_hi:[0,1]
	v_pk_add_f32 v[96:97], v[98:99], v[126:127]
	v_pk_add_f32 v[98:99], v[98:99], v[126:127] neg_lo:[0,1] neg_hi:[0,1]
	v_pk_add_f32 v[126:127], v[122:123], v[120:121]
	v_pk_add_f32 v[66:67], v[122:123], v[120:121] neg_lo:[0,1] neg_hi:[0,1]
	global_load_dwordx2 v[120:121], v[20:21], off
	v_pk_add_f32 v[122:123], v[108:109], v[128:129]
	v_pk_add_f32 v[108:109], v[108:109], v[128:129] neg_lo:[0,1] neg_hi:[0,1]
	v_pk_add_f32 v[128:129], v[110:111], v[124:125]
	v_pk_add_f32 v[72:73], v[110:111], v[124:125] neg_lo:[0,1] neg_hi:[0,1]
	global_load_dwordx2 v[110:111], v[22:23], off
	v_pk_add_f32 v[144:145], v[90:91], v[70:71]
	v_pk_add_f32 v[90:91], v[90:91], v[70:71] op_sel:[1,1] op_sel_hi:[0,0] neg_lo:[0,1] neg_hi:[1,0]
	v_pk_add_f32 v[124:125], v[100:101], v[112:113]
	v_pk_add_f32 v[100:101], v[100:101], v[112:113] neg_lo:[0,1] neg_hi:[0,1]
	v_pk_add_f32 v[112:113], v[102:103], v[106:107]
	v_pk_add_f32 v[70:71], v[102:103], v[106:107] neg_lo:[0,1] neg_hi:[0,1]
	global_load_dwordx2 v[102:103], v[24:25], off
	v_pk_add_f32 v[106:107], v[82:83], v[118:119]
	v_pk_add_f32 v[82:83], v[82:83], v[118:119] neg_lo:[0,1] neg_hi:[0,1]
	v_pk_add_f32 v[118:119], v[114:115], v[130:131]
	v_pk_add_f32 v[114:115], v[114:115], v[130:131] neg_lo:[0,1] neg_hi:[0,1]
	global_load_dwordx2 v[130:131], v[26:27], off
	v_pk_add_f32 v[162:163], v[76:77], v[90:91]
	v_pk_add_f32 v[76:77], v[76:77], v[90:91] neg_lo:[0,1] neg_hi:[0,1]
	v_pk_add_f32 v[90:91], v[146:147], v[150:151]
	v_pk_add_f32 v[146:147], v[146:147], v[150:151] neg_lo:[0,1] neg_hi:[0,1]
	v_pk_add_f32 v[150:151], v[78:79], v[152:153]
	v_pk_add_f32 v[78:79], v[78:79], v[152:153] neg_lo:[0,1] neg_hi:[0,1]
	global_load_dwordx2 v[152:153], v[34:35], off
	s_waitcnt vmcnt(19)
	v_pk_mul_f32 v[166:167], v[156:157], v[134:135] op_sel:[1,1] op_sel_hi:[0,1] neg_lo:[0,1]
	v_pk_add_f32 v[132:133], v[140:141], v[92:93]
	v_pk_fma_f32 v[134:135], v[156:157], v[134:135], v[166:167] op_sel_hi:[1,0,1]
	s_waitcnt vmcnt(18)
	global_load_dwordx2 v[166:167], v[38:39], off
	v_pk_mul_f32 v[156:157], v[106:107], v[136:137] op_sel:[1,1] op_sel_hi:[0,1] neg_lo:[0,1]
	v_pk_add_f32 v[92:93], v[140:141], v[92:93] neg_lo:[0,1] neg_hi:[0,1]
	v_pk_fma_f32 v[106:107], v[106:107], v[136:137], v[156:157] op_sel_hi:[1,0,1]
	s_waitcnt vmcnt(18)
	global_load_dwordx2 v[156:157], v[40:41], off
	v_pk_mul_f32 v[136:137], v[122:123], v[138:139] op_sel:[1,1] op_sel_hi:[0,1] neg_lo:[0,1]
	v_pk_add_f32 v[140:141], v[88:89], v[142:143]
	v_pk_fma_f32 v[122:123], v[122:123], v[138:139], v[136:137] op_sel_hi:[1,0,1]
	global_load_dwordx2 v[136:137], v[42:43], off
	v_pk_add_f32 v[88:89], v[88:89], v[142:143] neg_lo:[0,1] neg_hi:[0,1]
	v_pk_add_f32 v[142:143], v[74:75], v[144:145]
	v_pk_add_f32 v[74:75], v[74:75], v[144:145] neg_lo:[0,1] neg_hi:[0,1]
	global_load_dwordx2 v[144:145], v[30:31], off
	s_mov_b32 s11, s8
	s_waitcnt vmcnt(9)
	v_pk_mul_f32 v[138:139], v[142:143], v[84:85] op_sel:[1,1] op_sel_hi:[0,1] neg_lo:[0,1]
	v_pk_fma_f32 v[84:85], v[142:143], v[84:85], v[138:139] op_sel_hi:[1,0,1]
	global_load_dwordx2 v[142:143], v[46:47], off
	v_pk_mul_f32 v[138:139], v[96:97], v[86:87] op_sel:[1,1] op_sel_hi:[0,1] neg_lo:[0,1]
	v_pk_fma_f32 v[86:87], v[96:97], v[86:87], v[138:139] op_sel_hi:[1,0,1]
	global_load_dwordx2 v[138:139], v[48:49], off
	v_pk_mul_f32 v[96:97], v[132:133], v[94:95] op_sel:[1,1] op_sel_hi:[0,1] neg_lo:[0,1]
	v_pk_fma_f32 v[94:95], v[132:133], v[94:95], v[96:97] op_sel_hi:[1,0,1]
	global_load_dwordx2 v[96:97], v[50:51], off
	v_pk_mul_f32 v[132:133], v[124:125], v[148:149] op_sel:[1,1] op_sel_hi:[0,1] neg_lo:[0,1]
	v_pk_fma_f32 v[124:125], v[124:125], v[148:149], v[132:133] op_sel_hi:[1,0,1]
	global_load_dwordx2 v[148:149], v[54:55], off
	v_pk_mul_f32 v[132:133], v[90:91], v[154:155] op_sel:[1,1] op_sel_hi:[0,1] neg_lo:[0,1]
	v_pk_fma_f32 v[90:91], v[90:91], v[154:155], v[132:133] op_sel_hi:[1,0,1]
	global_load_dwordx2 v[154:155], v[56:57], off
	v_pk_mul_f32 v[132:133], v[116:117], v[158:159] op_sel:[1,1] op_sel_hi:[0,1] neg_lo:[0,1]
	v_pk_fma_f32 v[116:117], v[116:117], v[158:159], v[132:133] op_sel_hi:[1,0,1]
	global_load_dwordx2 v[132:133], v[58:59], off
	s_waitcnt vmcnt(14)
	v_pk_mul_f32 v[158:159], v[118:119], v[120:121] op_sel:[1,1] op_sel_hi:[0,1] neg_lo:[0,1]
	v_pk_fma_f32 v[118:119], v[118:119], v[120:121], v[158:159] op_sel_hi:[1,0,1]
	s_waitcnt vmcnt(13)
	global_load_dwordx2 v[158:159], v[62:63], off
	v_pk_mul_f32 v[120:121], v[128:129], v[110:111] op_sel:[1,1] op_sel_hi:[0,1] neg_lo:[0,1]
	v_pk_fma_f32 v[110:111], v[128:129], v[110:111], v[120:121] op_sel_hi:[1,0,1]
	global_load_dwordx2 v[128:129], v[64:65], off
	s_waitcnt vmcnt(14)
	v_pk_mul_f32 v[120:121], v[162:163], v[102:103] op_sel:[1,1] op_sel_hi:[0,1] neg_lo:[0,1]
	v_mov_b32 v0, 0
	s_nop 0
	v_pk_fma_f32 v[102:103], v[162:163], v[102:103], v[120:121] op_sel_hi:[1,0,1]
	s_waitcnt vmcnt(13)
	v_pk_mul_f32 v[120:121], v[126:127], v[130:131] op_sel:[1,1] op_sel_hi:[0,1] neg_lo:[0,1]
	v_pk_fma_f32 v[120:121], v[126:127], v[130:131], v[120:121] op_sel_hi:[1,0,1]
	v_pk_mul_f32 v[126:127], v[140:141], v[160:161] op_sel:[1,1] op_sel_hi:[0,1] neg_lo:[0,1]
	v_pk_fma_f32 v[126:127], v[140:141], v[160:161], v[126:127] op_sel_hi:[1,0,1]
	s_waitcnt vmcnt(12)
	v_pk_mul_f32 v[140:141], v[80:81], v[152:153] op_sel:[1,1] op_sel_hi:[0,1] neg_lo:[0,1]
	v_pk_fma_f32 v[80:81], v[80:81], v[152:153], v[140:141] op_sel_hi:[1,0,1]
	v_pk_mul_f32 v[140:141], v[82:83], v[168:169] op_sel:[1,1] op_sel_hi:[0,1] neg_lo:[0,1]
	v_pk_fma_f32 v[82:83], v[82:83], v[168:169], v[140:141] op_sel_hi:[1,0,1]
	s_waitcnt vmcnt(11)
	v_pk_mul_f32 v[140:141], v[108:109], v[166:167] op_sel:[1,1] op_sel_hi:[0,1] neg_lo:[0,1]
	v_pk_fma_f32 v[108:109], v[108:109], v[166:167], v[140:141] op_sel_hi:[1,0,1]
	s_waitcnt vmcnt(10)
	v_pk_mul_f32 v[140:141], v[74:75], v[156:157] op_sel:[1,1] op_sel_hi:[0,1] neg_lo:[0,1]
	v_pk_fma_f32 v[74:75], v[74:75], v[156:157], v[140:141] op_sel_hi:[1,0,1]
	s_waitcnt vmcnt(9)
	v_pk_mul_f32 v[140:141], v[98:99], v[136:137] op_sel:[1,1] op_sel_hi:[0,1] neg_lo:[0,1]
	v_pk_fma_f32 v[98:99], v[98:99], v[136:137], v[140:141] op_sel_hi:[1,0,1]
	v_pk_mul_f32 v[136:137], v[92:93], v[172:173] op_sel:[1,1] op_sel_hi:[0,1] neg_lo:[0,1]
	v_pk_fma_f32 v[92:93], v[92:93], v[172:173], v[136:137] op_sel_hi:[1,0,1]
	s_waitcnt vmcnt(8)
	v_pk_mul_f32 v[130:131], v[112:113], v[144:145] op_sel:[1,1] op_sel_hi:[0,1] neg_lo:[0,1]
	v_pk_fma_f32 v[112:113], v[112:113], v[144:145], v[130:131] op_sel_hi:[1,0,1]
	s_waitcnt vmcnt(7)
	v_pk_mul_f32 v[136:137], v[100:101], v[142:143] op_sel:[1,1] op_sel_hi:[0,1] neg_lo:[0,1]
	v_pk_fma_f32 v[100:101], v[100:101], v[142:143], v[136:137] op_sel_hi:[1,0,1]
	s_waitcnt vmcnt(6)
	v_pk_mul_f32 v[136:137], v[146:147], v[138:139] op_sel:[1,1] op_sel_hi:[0,1] neg_lo:[0,1]
	v_pk_fma_f32 v[136:137], v[146:147], v[138:139], v[136:137] op_sel_hi:[1,0,1]
	s_waitcnt vmcnt(5)
	v_pk_mul_f32 v[138:139], v[68:69], v[96:97] op_sel:[1,1] op_sel_hi:[0,1] neg_lo:[0,1]
	v_pk_fma_f32 v[68:69], v[68:69], v[96:97], v[138:139] op_sel_hi:[1,0,1]
	v_pk_mul_f32 v[96:97], v[114:115], v[174:175] op_sel:[1,1] op_sel_hi:[0,1] neg_lo:[0,1]
	v_pk_fma_f32 v[96:97], v[114:115], v[174:175], v[96:97] op_sel_hi:[1,0,1]
	s_waitcnt vmcnt(4)
	v_pk_mul_f32 v[114:115], v[72:73], v[148:149] op_sel:[1,1] op_sel_hi:[0,1] neg_lo:[0,1]
	v_pk_fma_f32 v[72:73], v[72:73], v[148:149], v[114:115] op_sel_hi:[1,0,1]
	v_pk_mul_f32 v[130:131], v[150:151], v[164:165] op_sel:[1,1] op_sel_hi:[0,1] neg_lo:[0,1]
	s_waitcnt vmcnt(3)
	v_pk_mul_f32 v[114:115], v[76:77], v[154:155] op_sel:[1,1] op_sel_hi:[0,1] neg_lo:[0,1]
	v_pk_fma_f32 v[76:77], v[76:77], v[154:155], v[114:115] op_sel_hi:[1,0,1]
	s_waitcnt vmcnt(2)
	v_pk_mul_f32 v[114:115], v[66:67], v[132:133] op_sel:[1,1] op_sel_hi:[0,1] neg_lo:[0,1]
	v_pk_fma_f32 v[66:67], v[66:67], v[132:133], v[114:115] op_sel_hi:[1,0,1]
	v_pk_mul_f32 v[114:115], v[88:89], v[176:177] op_sel:[1,1] op_sel_hi:[0,1] neg_lo:[0,1]
	v_pk_fma_f32 v[88:89], v[88:89], v[176:177], v[114:115] op_sel_hi:[1,0,1]
	s_waitcnt vmcnt(1)
	v_pk_mul_f32 v[114:115], v[70:71], v[158:159] op_sel:[1,1] op_sel_hi:[0,1] neg_lo:[0,1]
	v_pk_fma_f32 v[70:71], v[70:71], v[158:159], v[114:115] op_sel_hi:[1,0,1]
	s_waitcnt vmcnt(0)
	v_pk_mul_f32 v[114:115], v[78:79], v[128:129] op_sel:[1,1] op_sel_hi:[0,1] neg_lo:[0,1]
	v_pk_fma_f32 v[78:79], v[78:79], v[128:129], v[114:115] op_sel_hi:[1,0,1]
	v_pk_add_f32 v[128:129], v[106:107], v[82:83]
	v_pk_add_f32 v[82:83], v[106:107], v[82:83] neg_lo:[0,1] neg_hi:[0,1]
	v_pk_fma_f32 v[130:131], v[150:151], v[164:165], v[130:131] op_sel_hi:[1,0,1]
	v_pk_mul_f32 v[106:107], v[82:83], s[50:51]
	v_pk_add_f32 v[114:115], v[134:135], v[80:81]
	v_pk_fma_f32 v[82:83], v[82:83], s[20:21], v[106:107] op_sel:[0,0,1] op_sel_hi:[1,0,0]
	v_pk_add_f32 v[106:107], v[122:123], v[108:109]
	v_pk_add_f32 v[108:109], v[122:123], v[108:109] neg_lo:[0,1] neg_hi:[0,1]
	s_mov_b32 s21, s34
	v_pk_mul_f32 v[122:123], v[108:109], s[14:15]
	v_pk_add_f32 v[80:81], v[134:135], v[80:81] neg_lo:[0,1] neg_hi:[0,1]
	v_pk_fma_f32 v[108:109], v[108:109], s[6:7], v[122:123] op_sel:[0,0,1] op_sel_hi:[1,0,0]
	v_pk_add_f32 v[122:123], v[84:85], v[74:75]
	v_pk_add_f32 v[74:75], v[84:85], v[74:75] neg_lo:[0,1] neg_hi:[0,1]
	s_mov_b32 s7, s12
	v_pk_mul_f32 v[84:85], v[74:75], s[52:53]
	v_add_u32_e32 v0, v0, v170
	v_pk_fma_f32 v[74:75], v[74:75], s[24:25], v[84:85] op_sel:[0,0,1] op_sel_hi:[1,0,0]
	v_pk_add_f32 v[84:85], v[86:87], v[98:99]
	v_pk_add_f32 v[86:87], v[86:87], v[98:99] neg_lo:[0,1] neg_hi:[0,1]
	s_mov_b32 s25, s26
	v_pk_mul_f32 v[98:99], v[86:87], s[10:11]
	v_lshlrev_b32_e32 v105, 5, v0
	v_pk_fma_f32 v[86:87], v[86:87], s[10:11], v[98:99] op_sel:[0,0,1] op_sel_hi:[1,0,0]
	v_pk_add_f32 v[98:99], v[94:95], v[92:93]
	v_pk_add_f32 v[92:93], v[94:95], v[92:93] neg_lo:[0,1] neg_hi:[0,1]
	v_pk_mul_f32 v[94:95], v[92:93], s[24:25]
	v_pk_fma_f32 v[92:93], v[92:93], s[0:1], v[94:95] op_sel:[0,0,1] op_sel_hi:[1,0,0]
	v_pk_add_f32 v[94:95], v[124:125], v[100:101]
	v_pk_add_f32 v[100:101], v[124:125], v[100:101] neg_lo:[0,1] neg_hi:[0,1]
	v_pk_mul_f32 v[124:125], v[100:101], s[6:7]
	v_pk_fma_f32 v[100:101], v[100:101], s[14:15], v[124:125] op_sel:[0,0,1] op_sel_hi:[1,0,0]
	v_pk_add_f32 v[124:125], v[90:91], v[136:137]
	v_pk_add_f32 v[90:91], v[90:91], v[136:137] neg_lo:[0,1] neg_hi:[0,1]
	v_pk_mul_f32 v[132:133], v[90:91], s[20:21]
	v_pk_fma_f32 v[90:91], v[90:91], s[48:49], v[132:133] op_sel:[0,0,1] op_sel_hi:[1,0,0]
	v_pk_add_f32 v[132:133], v[116:117], v[68:69]
	v_pk_add_f32 v[116:117], v[116:117], v[68:69] op_sel:[1,1] op_sel_hi:[0,0] neg_lo:[1,0] neg_hi:[0,1]
	v_pk_add_f32 v[68:69], v[118:119], v[96:97]
	v_pk_add_f32 v[96:97], v[118:119], v[96:97] neg_lo:[0,1] neg_hi:[0,1]
	v_pk_mul_f32 v[118:119], v[96:97], s[20:21]
	v_pk_fma_f32 v[96:97], v[96:97], s[18:19], v[118:119] op_sel:[0,0,1] op_sel_hi:[1,0,0]
	v_pk_add_f32 v[118:119], v[110:111], v[72:73]
	v_pk_add_f32 v[72:73], v[110:111], v[72:73] neg_lo:[0,1] neg_hi:[0,1]
	v_pk_mul_f32 v[110:111], v[72:73], s[6:7]
	v_pk_fma_f32 v[72:73], v[72:73], s[4:5], v[110:111] op_sel:[0,0,1] op_sel_hi:[1,0,0]
	v_pk_add_f32 v[110:111], v[102:103], v[76:77]
	v_pk_add_f32 v[76:77], v[102:103], v[76:77] neg_lo:[0,1] neg_hi:[0,1]
	v_pk_mul_f32 v[102:103], v[76:77], s[24:25]
	v_pk_fma_f32 v[76:77], v[76:77], s[22:23], v[102:103] op_sel:[0,0,1] op_sel_hi:[1,0,0]
	v_pk_add_f32 v[102:103], v[120:121], v[66:67]
	v_pk_add_f32 v[66:67], v[120:121], v[66:67] neg_lo:[0,1] neg_hi:[0,1]
	v_pk_mul_f32 v[120:121], v[66:67], s[10:11]
	v_pk_fma_f32 v[66:67], v[66:67], s[8:9], v[120:121] op_sel:[0,0,1] op_sel_hi:[1,0,0]
	v_pk_add_f32 v[120:121], v[126:127], v[88:89]
	v_pk_add_f32 v[88:89], v[126:127], v[88:89] neg_lo:[0,1] neg_hi:[0,1]
	v_pk_mul_f32 v[126:127], v[88:89], s[52:53]
	v_pk_fma_f32 v[88:89], v[88:89], s[26:27], v[126:127] op_sel:[0,0,1] op_sel_hi:[1,0,0]
	v_pk_add_f32 v[126:127], v[112:113], v[70:71]
	v_pk_add_f32 v[70:71], v[112:113], v[70:71] neg_lo:[0,1] neg_hi:[0,1]
	v_pk_mul_f32 v[112:113], v[70:71], s[14:15]
	v_pk_fma_f32 v[70:71], v[70:71], s[12:13], v[112:113] op_sel:[0,0,1] op_sel_hi:[1,0,0]
	v_pk_add_f32 v[112:113], v[130:131], v[78:79]
	v_pk_add_f32 v[78:79], v[130:131], v[78:79] neg_lo:[0,1] neg_hi:[0,1]
	v_pk_mul_f32 v[130:131], v[78:79], s[50:51]
	v_pk_fma_f32 v[78:79], v[78:79], s[34:35], v[130:131] op_sel:[0,0,1] op_sel_hi:[1,0,0]
	v_pk_add_f32 v[130:131], v[114:115], v[132:133]
	v_pk_add_f32 v[114:115], v[114:115], v[132:133] neg_lo:[0,1] neg_hi:[0,1]
	v_pk_add_f32 v[132:133], v[128:129], v[68:69]
	v_pk_add_f32 v[68:69], v[128:129], v[68:69] neg_lo:[0,1] neg_hi:[0,1]
	v_pk_mul_f32 v[128:129], v[68:69], s[14:15]
	v_pk_fma_f32 v[68:69], v[68:69], s[6:7], v[128:129] op_sel:[0,0,1] op_sel_hi:[1,0,0]
	v_pk_add_f32 v[128:129], v[106:107], v[118:119]
	v_pk_add_f32 v[106:107], v[106:107], v[118:119] neg_lo:[0,1] neg_hi:[0,1]
	v_pk_mul_f32 v[118:119], v[106:107], s[10:11]
	v_pk_fma_f32 v[106:107], v[106:107], s[10:11], v[118:119] op_sel:[0,0,1] op_sel_hi:[1,0,0]
	v_pk_add_f32 v[118:119], v[122:123], v[110:111]
	v_pk_add_f32 v[110:111], v[122:123], v[110:111] neg_lo:[0,1] neg_hi:[0,1]
	v_pk_mul_f32 v[122:123], v[110:111], s[6:7]
	v_pk_fma_f32 v[110:111], v[110:111], s[14:15], v[122:123] op_sel:[0,0,1] op_sel_hi:[1,0,0]
	v_pk_add_f32 v[122:123], v[84:85], v[102:103]
	v_pk_add_f32 v[102:103], v[84:85], v[102:103] op_sel:[1,1] op_sel_hi:[0,0] neg_lo:[1,0] neg_hi:[0,1]
	v_pk_add_f32 v[84:85], v[98:99], v[120:121]
	v_pk_add_f32 v[98:99], v[98:99], v[120:121] neg_lo:[0,1] neg_hi:[0,1]
	v_pk_mul_f32 v[120:121], v[98:99], s[6:7]
	v_pk_fma_f32 v[98:99], v[98:99], s[4:5], v[120:121] op_sel:[0,0,1] op_sel_hi:[1,0,0]
	v_pk_add_f32 v[120:121], v[94:95], v[126:127]
	v_pk_add_f32 v[94:95], v[94:95], v[126:127] neg_lo:[0,1] neg_hi:[0,1]
	v_pk_mul_f32 v[126:127], v[94:95], s[10:11]
	v_pk_fma_f32 v[94:95], v[94:95], s[8:9], v[126:127] op_sel:[0,0,1] op_sel_hi:[1,0,0]
	v_pk_add_f32 v[126:127], v[124:125], v[112:113]
	v_pk_add_f32 v[112:113], v[124:125], v[112:113] neg_lo:[0,1] neg_hi:[0,1]
	v_pk_mul_f32 v[124:125], v[112:113], s[14:15]
	v_pk_fma_f32 v[112:113], v[112:113], s[12:13], v[124:125] op_sel:[0,0,1] op_sel_hi:[1,0,0]
	v_pk_add_f32 v[124:125], v[80:81], v[116:117]
	v_pk_add_f32 v[80:81], v[80:81], v[116:117] neg_lo:[0,1] neg_hi:[0,1]
	v_pk_add_f32 v[116:117], v[82:83], v[96:97]
	v_pk_add_f32 v[82:83], v[82:83], v[96:97] neg_lo:[0,1] neg_hi:[0,1]
	v_pk_mul_f32 v[96:97], v[82:83], s[14:15]
	v_pk_fma_f32 v[82:83], v[82:83], s[6:7], v[96:97] op_sel:[0,0,1] op_sel_hi:[1,0,0]
	v_pk_add_f32 v[96:97], v[108:109], v[72:73]
	v_pk_add_f32 v[72:73], v[108:109], v[72:73] neg_lo:[0,1] neg_hi:[0,1]
	v_pk_mul_f32 v[108:109], v[72:73], s[10:11]
	v_pk_fma_f32 v[72:73], v[72:73], s[10:11], v[108:109] op_sel:[0,0,1] op_sel_hi:[1,0,0]
	v_pk_add_f32 v[108:109], v[74:75], v[76:77]
	v_pk_add_f32 v[74:75], v[74:75], v[76:77] neg_lo:[0,1] neg_hi:[0,1]
	v_pk_mul_f32 v[76:77], v[74:75], s[6:7]
	v_pk_fma_f32 v[74:75], v[74:75], s[14:15], v[76:77] op_sel:[0,0,1] op_sel_hi:[1,0,0]
	v_pk_add_f32 v[76:77], v[86:87], v[66:67]
	v_pk_add_f32 v[86:87], v[86:87], v[66:67] op_sel:[1,1] op_sel_hi:[0,0] neg_lo:[1,0] neg_hi:[0,1]
	v_pk_add_f32 v[66:67], v[92:93], v[88:89]
	v_pk_add_f32 v[88:89], v[92:93], v[88:89] neg_lo:[0,1] neg_hi:[0,1]
	v_pk_mul_f32 v[92:93], v[88:89], s[6:7]
	v_pk_fma_f32 v[88:89], v[88:89], s[4:5], v[92:93] op_sel:[0,0,1] op_sel_hi:[1,0,0]
	v_pk_add_f32 v[92:93], v[100:101], v[70:71]
	v_pk_add_f32 v[70:71], v[100:101], v[70:71] neg_lo:[0,1] neg_hi:[0,1]
	v_pk_mul_f32 v[100:101], v[70:71], s[10:11]
	v_pk_fma_f32 v[70:71], v[70:71], s[8:9], v[100:101] op_sel:[0,0,1] op_sel_hi:[1,0,0]
	v_pk_add_f32 v[100:101], v[90:91], v[78:79]
	v_pk_add_f32 v[78:79], v[90:91], v[78:79] neg_lo:[0,1] neg_hi:[0,1]
	v_pk_mul_f32 v[90:91], v[78:79], s[14:15]
	v_pk_fma_f32 v[78:79], v[78:79], s[12:13], v[90:91] op_sel:[0,0,1] op_sel_hi:[1,0,0]
	v_pk_add_f32 v[90:91], v[130:131], v[122:123]
	v_pk_add_f32 v[122:123], v[130:131], v[122:123] neg_lo:[0,1] neg_hi:[0,1]
	v_pk_add_f32 v[130:131], v[132:133], v[84:85]
	v_pk_add_f32 v[84:85], v[132:133], v[84:85] neg_lo:[0,1] neg_hi:[0,1]
	v_pk_mul_f32 v[132:133], v[84:85], s[10:11]
	v_pk_fma_f32 v[84:85], v[84:85], s[10:11], v[132:133] op_sel:[0,0,1] op_sel_hi:[1,0,0]
	v_pk_add_f32 v[132:133], v[128:129], v[120:121]
	v_pk_add_f32 v[128:129], v[128:129], v[120:121] op_sel:[1,1] op_sel_hi:[0,0] neg_lo:[1,0] neg_hi:[0,1]
	v_pk_add_f32 v[120:121], v[118:119], v[126:127]
	v_pk_add_f32 v[118:119], v[118:119], v[126:127] neg_lo:[0,1] neg_hi:[0,1]
	v_pk_mul_f32 v[126:127], v[118:119], s[10:11]
	v_pk_fma_f32 v[118:119], v[118:119], s[8:9], v[126:127] op_sel:[0,0,1] op_sel_hi:[1,0,0]
	v_pk_add_f32 v[126:127], v[114:115], v[102:103]
	v_pk_add_f32 v[102:103], v[114:115], v[102:103] neg_lo:[0,1] neg_hi:[0,1]
	v_pk_add_f32 v[114:115], v[68:69], v[98:99]
	v_pk_add_f32 v[68:69], v[68:69], v[98:99] neg_lo:[0,1] neg_hi:[0,1]
	v_pk_mul_f32 v[98:99], v[68:69], s[10:11]
	v_pk_fma_f32 v[68:69], v[68:69], s[10:11], v[98:99] op_sel:[0,0,1] op_sel_hi:[1,0,0]
	v_pk_add_f32 v[98:99], v[106:107], v[94:95]
	v_pk_add_f32 v[106:107], v[106:107], v[94:95] op_sel:[1,1] op_sel_hi:[0,0] neg_lo:[1,0] neg_hi:[0,1]
	v_pk_add_f32 v[94:95], v[110:111], v[112:113]
	v_pk_add_f32 v[110:111], v[110:111], v[112:113] neg_lo:[0,1] neg_hi:[0,1]
	v_pk_mul_f32 v[112:113], v[110:111], s[10:11]
	v_pk_fma_f32 v[110:111], v[110:111], s[8:9], v[112:113] op_sel:[0,0,1] op_sel_hi:[1,0,0]
	v_pk_add_f32 v[112:113], v[124:125], v[76:77]
	v_pk_add_f32 v[76:77], v[124:125], v[76:77] neg_lo:[0,1] neg_hi:[0,1]
	v_pk_add_f32 v[124:125], v[116:117], v[66:67]
	v_pk_add_f32 v[66:67], v[116:117], v[66:67] neg_lo:[0,1] neg_hi:[0,1]
	v_pk_mul_f32 v[116:117], v[66:67], s[10:11]
	v_pk_fma_f32 v[66:67], v[66:67], s[10:11], v[116:117] op_sel:[0,0,1] op_sel_hi:[1,0,0]
	v_pk_add_f32 v[116:117], v[96:97], v[92:93]
	v_pk_add_f32 v[96:97], v[96:97], v[92:93] op_sel:[1,1] op_sel_hi:[0,0] neg_lo:[1,0] neg_hi:[0,1]
	v_pk_add_f32 v[134:135], v[112:113], v[116:117]
	v_pk_add_f32 v[92:93], v[108:109], v[100:101]
	v_pk_add_f32 v[100:101], v[108:109], v[100:101] neg_lo:[0,1] neg_hi:[0,1]
	v_pk_add_f32 v[112:113], v[112:113], v[116:117] neg_lo:[0,1] neg_hi:[0,1]
	v_pk_mul_f32 v[108:109], v[100:101], s[10:11]
	v_pk_add_f32 v[116:117], v[124:125], v[92:93]
	v_pk_fma_f32 v[100:101], v[100:101], s[8:9], v[108:109] op_sel:[0,0,1] op_sel_hi:[1,0,0]
	v_pk_add_f32 v[108:109], v[80:81], v[86:87]
	v_pk_add_f32 v[80:81], v[80:81], v[86:87] neg_lo:[0,1] neg_hi:[0,1]
	v_pk_add_f32 v[86:87], v[82:83], v[88:89]
	v_pk_add_f32 v[82:83], v[82:83], v[88:89] neg_lo:[0,1] neg_hi:[0,1]
	v_pk_mul_f32 v[88:89], v[82:83], s[10:11]
	v_pk_fma_f32 v[82:83], v[82:83], s[10:11], v[88:89] op_sel:[0,0,1] op_sel_hi:[1,0,0]
	v_pk_add_f32 v[88:89], v[72:73], v[70:71]
	v_pk_add_f32 v[72:73], v[72:73], v[70:71] op_sel:[1,1] op_sel_hi:[0,0] neg_lo:[1,0] neg_hi:[0,1]
	v_pk_add_f32 v[136:137], v[108:109], v[88:89]
	v_pk_add_f32 v[70:71], v[74:75], v[78:79]
	v_pk_add_f32 v[74:75], v[74:75], v[78:79] neg_lo:[0,1] neg_hi:[0,1]
	v_pk_add_f32 v[88:89], v[108:109], v[88:89] neg_lo:[0,1] neg_hi:[0,1]
	v_pk_mul_f32 v[78:79], v[74:75], s[10:11]
	v_pk_add_f32 v[108:109], v[86:87], v[70:71]
	v_pk_fma_f32 v[74:75], v[74:75], s[8:9], v[78:79] op_sel:[0,0,1] op_sel_hi:[1,0,0]
	v_pk_add_f32 v[78:79], v[90:91], v[132:133]
	v_pk_add_f32 v[90:91], v[90:91], v[132:133] neg_lo:[0,1] neg_hi:[0,1]
	v_pk_add_f32 v[132:133], v[130:131], v[120:121]
	v_pk_add_f32 v[130:131], v[130:131], v[120:121] op_sel:[1,1] op_sel_hi:[0,0] neg_lo:[1,0] neg_hi:[0,1]
	v_pk_add_f32 v[138:139], v[80:81], v[72:73] neg_lo:[0,1] neg_hi:[0,1]
	v_pk_add_f32 v[120:121], v[122:123], v[128:129]
	v_pk_add_f32 v[122:123], v[122:123], v[128:129] neg_lo:[0,1] neg_hi:[0,1]
	v_pk_add_f32 v[128:129], v[84:85], v[118:119]
	v_pk_add_f32 v[118:119], v[84:85], v[118:119] op_sel:[1,1] op_sel_hi:[0,0] neg_lo:[1,0] neg_hi:[0,1]
	v_pk_add_f32 v[140:141], v[82:83], v[74:75]
	v_pk_add_f32 v[84:85], v[126:127], v[98:99]
	v_pk_add_f32 v[98:99], v[126:127], v[98:99] neg_lo:[0,1] neg_hi:[0,1]
	v_pk_add_f32 v[126:127], v[114:115], v[94:95]
	v_pk_add_f32 v[114:115], v[114:115], v[94:95] op_sel:[1,1] op_sel_hi:[0,0] neg_lo:[1,0] neg_hi:[0,1]
	v_pk_add_f32 v[142:143], v[78:79], v[132:133]
	v_pk_add_f32 v[94:95], v[102:103], v[106:107]
	v_pk_add_f32 v[102:103], v[102:103], v[106:107] neg_lo:[0,1] neg_hi:[0,1]
	v_pk_add_f32 v[106:107], v[68:69], v[110:111]
	v_pk_add_f32 v[110:111], v[68:69], v[110:111] op_sel:[1,1] op_sel_hi:[0,0] neg_lo:[1,0] neg_hi:[0,1]
	v_pk_add_f32 v[132:133], v[78:79], v[132:133] neg_lo:[0,1] neg_hi:[0,1]
	v_pk_add_f32 v[92:93], v[124:125], v[92:93] op_sel:[1,1] op_sel_hi:[0,0] neg_lo:[1,0] neg_hi:[0,1]
	v_pk_add_f32 v[124:125], v[76:77], v[96:97]
	v_pk_add_f32 v[76:77], v[76:77], v[96:97] neg_lo:[0,1] neg_hi:[0,1]
	v_pk_add_f32 v[96:97], v[66:67], v[100:101]
	v_pk_add_f32 v[100:101], v[66:67], v[100:101] op_sel:[1,1] op_sel_hi:[0,0] neg_lo:[1,0] neg_hi:[0,1]
	v_pk_add_f32 v[70:71], v[86:87], v[70:71] op_sel:[1,1] op_sel_hi:[0,0] neg_lo:[1,0] neg_hi:[0,1]
	v_pk_add_f32 v[74:75], v[82:83], v[74:75] op_sel:[1,1] op_sel_hi:[0,0] neg_lo:[1,0] neg_hi:[0,1]
	v_pk_add_f32 v[86:87], v[80:81], v[72:73]
	v_pk_add_f32 v[144:145], v[90:91], v[130:131]
	v_pk_add_f32 v[82:83], v[90:91], v[130:131] neg_lo:[0,1] neg_hi:[0,1]
	v_pk_add_f32 v[90:91], v[120:121], v[128:129]
	v_pk_add_f32 v[120:121], v[120:121], v[128:129] neg_lo:[0,1] neg_hi:[0,1]
	v_pk_add_f32 v[128:129], v[122:123], v[118:119]
	v_pk_add_f32 v[68:69], v[122:123], v[118:119] neg_lo:[0,1] neg_hi:[0,1]
	v_pk_add_f32 v[118:119], v[84:85], v[126:127]
	v_pk_add_f32 v[122:123], v[84:85], v[126:127] neg_lo:[0,1] neg_hi:[0,1]
	v_pk_add_f32 v[126:127], v[98:99], v[114:115]
	v_pk_add_f32 v[78:79], v[98:99], v[114:115] neg_lo:[0,1] neg_hi:[0,1]
	v_pk_add_f32 v[98:99], v[94:95], v[106:107]
	v_pk_add_f32 v[94:95], v[94:95], v[106:107] neg_lo:[0,1] neg_hi:[0,1]
	v_pk_add_f32 v[106:107], v[102:103], v[110:111]
	v_pk_add_f32 v[66:67], v[102:103], v[110:111] neg_lo:[0,1] neg_hi:[0,1]
	v_pk_add_f32 v[102:103], v[134:135], v[116:117]
	v_pk_add_f32 v[110:111], v[134:135], v[116:117] neg_lo:[0,1] neg_hi:[0,1]
	v_pk_add_f32 v[116:117], v[88:89], v[70:71]
	v_pk_add_f32 v[80:81], v[88:89], v[70:71] neg_lo:[0,1] neg_hi:[0,1]
	v_lshlrev_b32_e32 v70, 4, v0
	v_and_b32_e32 v70, 0x1f0, v70
	v_pk_add_f32 v[114:115], v[112:113], v[92:93]
	v_pk_add_f32 v[84:85], v[112:113], v[92:93] neg_lo:[0,1] neg_hi:[0,1]
	v_pk_add_f32 v[112:113], v[76:77], v[100:101]
	v_pk_add_f32 v[72:73], v[76:77], v[100:101] neg_lo:[0,1] neg_hi:[0,1]
	v_cvt_f32_u32_e32 v76, v70
	v_pk_add_f32 v[92:93], v[124:125], v[96:97]
	v_pk_add_f32 v[96:97], v[124:125], v[96:97] neg_lo:[0,1] neg_hi:[0,1]
	v_pk_add_f32 v[124:125], v[138:139], v[74:75]
	v_mul_f32_e32 v76, 0x38800000, v76
	v_pk_add_f32 v[70:71], v[138:139], v[74:75] neg_lo:[0,1] neg_hi:[0,1]
	v_sin_f32_e32 v75, v76
	v_ashrrev_i32_e32 v74, 2, v105
	v_lshlrev_b32_e32 v0, 8, v0
	v_add3_u32 v0, 0, v74, v0
	v_cos_f32_e32 v74, v76
	v_xor_b32_e32 v76, 0x80000000, v75
	v_mov_b32_e32 v77, v75
	v_pk_mul_f32 v[130:131], v[76:77], v[102:103] op_sel:[0,1] op_sel_hi:[1,0]
	v_pk_add_f32 v[100:101], v[136:137], v[108:109]
	v_pk_fma_f32 v[102:103], v[102:103], v[74:75], v[130:131] op_sel_hi:[1,0,1]
	ds_write2_b64 v0, v[142:143], v[102:103] offset1:1
	v_pk_mul_f32 v[102:103], v[76:77], v[74:75] op_sel:[0,1] op_sel_hi:[1,0]
	v_pk_add_f32 v[88:89], v[86:87], v[140:141]
	v_pk_fma_f32 v[102:103], v[74:75], v[74:75], v[102:103] op_sel_hi:[1,0,1]
	v_pk_add_f32 v[108:109], v[136:137], v[108:109] neg_lo:[0,1] neg_hi:[0,1]
	v_pk_mul_f32 v[130:131], v[118:119], v[102:103] op_sel:[1,1] op_sel_hi:[0,1] neg_lo:[0,1]
	v_pk_fma_f32 v[118:119], v[118:119], v[102:103], v[130:131] op_sel_hi:[1,0,1]
	v_pk_mul_f32 v[130:131], v[76:77], v[102:103] op_sel:[0,1] op_sel_hi:[1,0]
	v_pk_add_f32 v[86:87], v[86:87], v[140:141] neg_lo:[0,1] neg_hi:[0,1]
	v_pk_fma_f32 v[102:103], v[102:103], v[74:75], v[130:131] op_sel_hi:[1,0,1]
	v_pk_mul_f32 v[130:131], v[100:101], v[102:103] op_sel:[1,1] op_sel_hi:[0,1] neg_lo:[0,1]
	v_pk_fma_f32 v[100:101], v[100:101], v[102:103], v[130:131] op_sel_hi:[1,0,1]
	ds_write2_b64 v0, v[118:119], v[100:101] offset0:2 offset1:3
	v_pk_mul_f32 v[100:101], v[76:77], v[102:103] op_sel:[0,1] op_sel_hi:[1,0]
	v_pk_fma_f32 v[100:101], v[102:103], v[74:75], v[100:101] op_sel_hi:[1,0,1]
	v_pk_mul_f32 v[102:103], v[90:91], v[100:101] op_sel:[1,1] op_sel_hi:[0,1] neg_lo:[0,1]
	v_pk_fma_f32 v[90:91], v[90:91], v[100:101], v[102:103] op_sel_hi:[1,0,1]
	v_pk_mul_f32 v[102:103], v[76:77], v[100:101] op_sel:[0,1] op_sel_hi:[1,0]
	v_pk_fma_f32 v[100:101], v[100:101], v[74:75], v[102:103] op_sel_hi:[1,0,1]
	v_pk_mul_f32 v[102:103], v[92:93], v[100:101] op_sel:[1,1] op_sel_hi:[0,1] neg_lo:[0,1]
	v_pk_fma_f32 v[92:93], v[92:93], v[100:101], v[102:103] op_sel_hi:[1,0,1]
	ds_write2_b64 v0, v[90:91], v[92:93] offset0:4 offset1:5
	v_pk_mul_f32 v[90:91], v[76:77], v[100:101] op_sel:[0,1] op_sel_hi:[1,0]
	v_pk_fma_f32 v[90:91], v[100:101], v[74:75], v[90:91] op_sel_hi:[1,0,1]
	v_pk_mul_f32 v[92:93], v[98:99], v[90:91] op_sel:[1,1] op_sel_hi:[0,1] neg_lo:[0,1]
	v_pk_fma_f32 v[92:93], v[98:99], v[90:91], v[92:93] op_sel_hi:[1,0,1]
	v_pk_mul_f32 v[98:99], v[76:77], v[90:91] op_sel:[0,1] op_sel_hi:[1,0]
	v_pk_fma_f32 v[90:91], v[90:91], v[74:75], v[98:99] op_sel_hi:[1,0,1]
	v_pk_mul_f32 v[98:99], v[88:89], v[90:91] op_sel:[1,1] op_sel_hi:[0,1] neg_lo:[0,1]
	v_pk_fma_f32 v[88:89], v[88:89], v[90:91], v[98:99] op_sel_hi:[1,0,1]
	ds_write2_b64 v0, v[92:93], v[88:89] offset0:6 offset1:7
	v_pk_mul_f32 v[88:89], v[76:77], v[90:91] op_sel:[0,1] op_sel_hi:[1,0]
	v_pk_fma_f32 v[88:89], v[90:91], v[74:75], v[88:89] op_sel_hi:[1,0,1]
	v_pk_mul_f32 v[90:91], v[144:145], v[88:89] op_sel:[1,1] op_sel_hi:[0,1] neg_lo:[0,1]
	v_pk_mul_f32 v[92:93], v[76:77], v[88:89] op_sel:[0,1] op_sel_hi:[1,0]
	v_pk_fma_f32 v[90:91], v[144:145], v[88:89], v[90:91] op_sel_hi:[1,0,1]
	v_pk_fma_f32 v[88:89], v[88:89], v[74:75], v[92:93] op_sel_hi:[1,0,1]
	v_pk_mul_f32 v[92:93], v[114:115], v[88:89] op_sel:[1,1] op_sel_hi:[0,1] neg_lo:[0,1]
	v_pk_fma_f32 v[92:93], v[114:115], v[88:89], v[92:93] op_sel_hi:[1,0,1]
	ds_write2_b64 v0, v[90:91], v[92:93] offset0:8 offset1:9
	v_pk_mul_f32 v[90:91], v[76:77], v[88:89] op_sel:[0,1] op_sel_hi:[1,0]
	v_pk_fma_f32 v[88:89], v[88:89], v[74:75], v[90:91] op_sel_hi:[1,0,1]
	v_pk_mul_f32 v[90:91], v[126:127], v[88:89] op_sel:[1,1] op_sel_hi:[0,1] neg_lo:[0,1]
	v_pk_mul_f32 v[92:93], v[76:77], v[88:89] op_sel:[0,1] op_sel_hi:[1,0]
	v_pk_fma_f32 v[90:91], v[126:127], v[88:89], v[90:91] op_sel_hi:[1,0,1]
	v_pk_fma_f32 v[88:89], v[88:89], v[74:75], v[92:93] op_sel_hi:[1,0,1]
	v_pk_mul_f32 v[92:93], v[116:117], v[88:89] op_sel:[1,1] op_sel_hi:[0,1] neg_lo:[0,1]
	v_pk_fma_f32 v[92:93], v[116:117], v[88:89], v[92:93] op_sel_hi:[1,0,1]
	ds_write2_b64 v0, v[90:91], v[92:93] offset0:10 offset1:11
	v_pk_mul_f32 v[90:91], v[76:77], v[88:89] op_sel:[0,1] op_sel_hi:[1,0]
	v_pk_fma_f32 v[88:89], v[88:89], v[74:75], v[90:91] op_sel_hi:[1,0,1]
	v_pk_mul_f32 v[90:91], v[128:129], v[88:89] op_sel:[1,1] op_sel_hi:[0,1] neg_lo:[0,1]
	v_pk_mul_f32 v[92:93], v[76:77], v[88:89] op_sel:[0,1] op_sel_hi:[1,0]
	v_pk_fma_f32 v[90:91], v[128:129], v[88:89], v[90:91] op_sel_hi:[1,0,1]
	v_pk_fma_f32 v[88:89], v[88:89], v[74:75], v[92:93] op_sel_hi:[1,0,1]
	v_pk_mul_f32 v[92:93], v[112:113], v[88:89] op_sel:[1,1] op_sel_hi:[0,1] neg_lo:[0,1]
	v_pk_fma_f32 v[92:93], v[112:113], v[88:89], v[92:93] op_sel_hi:[1,0,1]
	ds_write2_b64 v0, v[90:91], v[92:93] offset0:12 offset1:13
	v_pk_mul_f32 v[90:91], v[76:77], v[88:89] op_sel:[0,1] op_sel_hi:[1,0]
	v_pk_fma_f32 v[88:89], v[88:89], v[74:75], v[90:91] op_sel_hi:[1,0,1]
	v_pk_mul_f32 v[90:91], v[106:107], v[88:89] op_sel:[1,1] op_sel_hi:[0,1] neg_lo:[0,1]
	v_pk_mul_f32 v[92:93], v[76:77], v[88:89] op_sel:[0,1] op_sel_hi:[1,0]
	v_pk_fma_f32 v[90:91], v[106:107], v[88:89], v[90:91] op_sel_hi:[1,0,1]
	v_pk_fma_f32 v[88:89], v[88:89], v[74:75], v[92:93] op_sel_hi:[1,0,1]
	v_pk_mul_f32 v[92:93], v[124:125], v[88:89] op_sel:[1,1] op_sel_hi:[0,1] neg_lo:[0,1]
	v_pk_fma_f32 v[92:93], v[124:125], v[88:89], v[92:93] op_sel_hi:[1,0,1]
	ds_write2_b64 v0, v[90:91], v[92:93] offset0:14 offset1:15
	v_pk_mul_f32 v[90:91], v[76:77], v[88:89] op_sel:[0,1] op_sel_hi:[1,0]
	v_pk_fma_f32 v[88:89], v[88:89], v[74:75], v[90:91] op_sel_hi:[1,0,1]
	v_pk_mul_f32 v[90:91], v[132:133], v[88:89] op_sel:[1,1] op_sel_hi:[0,1] neg_lo:[0,1]
	v_pk_mul_f32 v[92:93], v[76:77], v[88:89] op_sel:[0,1] op_sel_hi:[1,0]
	v_pk_fma_f32 v[90:91], v[132:133], v[88:89], v[90:91] op_sel_hi:[1,0,1]
	v_pk_fma_f32 v[88:89], v[88:89], v[74:75], v[92:93] op_sel_hi:[1,0,1]
	v_pk_mul_f32 v[92:93], v[110:111], v[88:89] op_sel:[1,1] op_sel_hi:[0,1] neg_lo:[0,1]
	v_pk_fma_f32 v[92:93], v[110:111], v[88:89], v[92:93] op_sel_hi:[1,0,1]
	ds_write2_b64 v0, v[90:91], v[92:93] offset0:16 offset1:17
	v_pk_mul_f32 v[90:91], v[76:77], v[88:89] op_sel:[0,1] op_sel_hi:[1,0]
	v_pk_fma_f32 v[88:89], v[88:89], v[74:75], v[90:91] op_sel_hi:[1,0,1]
	v_pk_mul_f32 v[90:91], v[122:123], v[88:89] op_sel:[1,1] op_sel_hi:[0,1] neg_lo:[0,1]
	v_pk_mul_f32 v[92:93], v[76:77], v[88:89] op_sel:[0,1] op_sel_hi:[1,0]
	v_pk_fma_f32 v[90:91], v[122:123], v[88:89], v[90:91] op_sel_hi:[1,0,1]
	v_pk_fma_f32 v[88:89], v[88:89], v[74:75], v[92:93] op_sel_hi:[1,0,1]
	v_pk_mul_f32 v[92:93], v[108:109], v[88:89] op_sel:[1,1] op_sel_hi:[0,1] neg_lo:[0,1]
	v_pk_fma_f32 v[92:93], v[108:109], v[88:89], v[92:93] op_sel_hi:[1,0,1]
	ds_write2_b64 v0, v[90:91], v[92:93] offset0:18 offset1:19
	v_pk_mul_f32 v[90:91], v[76:77], v[88:89] op_sel:[0,1] op_sel_hi:[1,0]
	v_pk_fma_f32 v[88:89], v[88:89], v[74:75], v[90:91] op_sel_hi:[1,0,1]
	v_pk_mul_f32 v[90:91], v[120:121], v[88:89] op_sel:[1,1] op_sel_hi:[0,1] neg_lo:[0,1]
	v_pk_mul_f32 v[92:93], v[76:77], v[88:89] op_sel:[0,1] op_sel_hi:[1,0]
	v_pk_fma_f32 v[90:91], v[120:121], v[88:89], v[90:91] op_sel_hi:[1,0,1]
	v_pk_fma_f32 v[88:89], v[88:89], v[74:75], v[92:93] op_sel_hi:[1,0,1]
	v_pk_mul_f32 v[92:93], v[96:97], v[88:89] op_sel:[1,1] op_sel_hi:[0,1] neg_lo:[0,1]
	v_pk_fma_f32 v[92:93], v[96:97], v[88:89], v[92:93] op_sel_hi:[1,0,1]
	ds_write2_b64 v0, v[90:91], v[92:93] offset0:20 offset1:21
	v_pk_mul_f32 v[90:91], v[76:77], v[88:89] op_sel:[0,1] op_sel_hi:[1,0]
	v_pk_fma_f32 v[88:89], v[88:89], v[74:75], v[90:91] op_sel_hi:[1,0,1]
	v_pk_mul_f32 v[90:91], v[94:95], v[88:89] op_sel:[1,1] op_sel_hi:[0,1] neg_lo:[0,1]
	v_pk_mul_f32 v[92:93], v[76:77], v[88:89] op_sel:[0,1] op_sel_hi:[1,0]
	v_pk_fma_f32 v[90:91], v[94:95], v[88:89], v[90:91] op_sel_hi:[1,0,1]
	v_pk_fma_f32 v[88:89], v[88:89], v[74:75], v[92:93] op_sel_hi:[1,0,1]
	v_pk_mul_f32 v[92:93], v[86:87], v[88:89] op_sel:[1,1] op_sel_hi:[0,1] neg_lo:[0,1]
	v_pk_fma_f32 v[86:87], v[86:87], v[88:89], v[92:93] op_sel_hi:[1,0,1]
	ds_write2_b64 v0, v[90:91], v[86:87] offset0:22 offset1:23
	v_pk_mul_f32 v[86:87], v[76:77], v[88:89] op_sel:[0,1] op_sel_hi:[1,0]
	v_pk_fma_f32 v[86:87], v[88:89], v[74:75], v[86:87] op_sel_hi:[1,0,1]
	v_pk_mul_f32 v[88:89], v[82:83], v[86:87] op_sel:[1,1] op_sel_hi:[0,1] neg_lo:[0,1]
	v_pk_fma_f32 v[82:83], v[82:83], v[86:87], v[88:89] op_sel_hi:[1,0,1]
	v_pk_mul_f32 v[88:89], v[76:77], v[86:87] op_sel:[0,1] op_sel_hi:[1,0]
	v_pk_fma_f32 v[86:87], v[86:87], v[74:75], v[88:89] op_sel_hi:[1,0,1]
	v_pk_mul_f32 v[88:89], v[84:85], v[86:87] op_sel:[1,1] op_sel_hi:[0,1] neg_lo:[0,1]
	v_pk_fma_f32 v[84:85], v[84:85], v[86:87], v[88:89] op_sel_hi:[1,0,1]
	ds_write2_b64 v0, v[82:83], v[84:85] offset0:24 offset1:25
	v_pk_mul_f32 v[82:83], v[76:77], v[86:87] op_sel:[0,1] op_sel_hi:[1,0]
	v_pk_fma_f32 v[82:83], v[86:87], v[74:75], v[82:83] op_sel_hi:[1,0,1]
	v_pk_mul_f32 v[84:85], v[78:79], v[82:83] op_sel:[1,1] op_sel_hi:[0,1] neg_lo:[0,1]
	v_pk_fma_f32 v[78:79], v[78:79], v[82:83], v[84:85] op_sel_hi:[1,0,1]
	v_pk_mul_f32 v[84:85], v[76:77], v[82:83] op_sel:[0,1] op_sel_hi:[1,0]
	v_pk_fma_f32 v[82:83], v[82:83], v[74:75], v[84:85] op_sel_hi:[1,0,1]
	v_pk_mul_f32 v[84:85], v[80:81], v[82:83] op_sel:[1,1] op_sel_hi:[0,1] neg_lo:[0,1]
	v_pk_fma_f32 v[80:81], v[80:81], v[82:83], v[84:85] op_sel_hi:[1,0,1]
	ds_write2_b64 v0, v[78:79], v[80:81] offset0:26 offset1:27
	v_pk_mul_f32 v[78:79], v[76:77], v[82:83] op_sel:[0,1] op_sel_hi:[1,0]
	v_pk_fma_f32 v[78:79], v[82:83], v[74:75], v[78:79] op_sel_hi:[1,0,1]
	v_pk_mul_f32 v[80:81], v[68:69], v[78:79] op_sel:[1,1] op_sel_hi:[0,1] neg_lo:[0,1]
	v_pk_fma_f32 v[68:69], v[68:69], v[78:79], v[80:81] op_sel_hi:[1,0,1]
	v_pk_mul_f32 v[80:81], v[76:77], v[78:79] op_sel:[0,1] op_sel_hi:[1,0]
	v_pk_fma_f32 v[78:79], v[78:79], v[74:75], v[80:81] op_sel_hi:[1,0,1]
	v_pk_mul_f32 v[80:81], v[72:73], v[78:79] op_sel:[1,1] op_sel_hi:[0,1] neg_lo:[0,1]
	v_pk_fma_f32 v[72:73], v[72:73], v[78:79], v[80:81] op_sel_hi:[1,0,1]
	ds_write2_b64 v0, v[68:69], v[72:73] offset0:28 offset1:29
	v_pk_mul_f32 v[68:69], v[76:77], v[78:79] op_sel:[0,1] op_sel_hi:[1,0]
	v_pk_fma_f32 v[68:69], v[78:79], v[74:75], v[68:69] op_sel_hi:[1,0,1]
	v_pk_mul_f32 v[72:73], v[66:67], v[68:69] op_sel:[1,1] op_sel_hi:[0,1] neg_lo:[0,1]
	v_pk_fma_f32 v[66:67], v[66:67], v[68:69], v[72:73] op_sel_hi:[1,0,1]
	v_pk_mul_f32 v[72:73], v[76:77], v[68:69] op_sel:[0,1] op_sel_hi:[1,0]
	v_pk_fma_f32 v[68:69], v[68:69], v[74:75], v[72:73] op_sel_hi:[1,0,1]
	v_pk_mul_f32 v[72:73], v[70:71], v[68:69] op_sel:[1,1] op_sel_hi:[0,1] neg_lo:[0,1]
	v_pk_fma_f32 v[68:69], v[70:71], v[68:69], v[72:73] op_sel_hi:[1,0,1]
	ds_write2_b64 v0, v[66:67], v[68:69] offset0:30 offset1:31
	s_waitcnt lgkmcnt(0)
	s_barrier
	v_mov_b32 v0, 0
	s_nop 0
	v_add_u32_e32 v71, v0, v170
	v_ashrrev_i32_e32 v105, 5, v71
	v_lshlrev_b32_e32 v0, 10, v105
	v_and_b32_e32 v140, 31, v71
	v_ashrrev_i32_e32 v0, 2, v0
	v_lshlrev_b32_e32 v67, 13, v105
	v_lshlrev_b32_e32 v68, 3, v140
	v_add_u32_e32 v0, 0, v0
	v_lshl_add_u32 v66, v105, 8, 0
	v_add3_u32 v0, v0, v67, v68
	v_add3_u32 v142, v66, v67, v68
	v_add_u32_e32 v143, 0x400, v0
	v_add_u32_e32 v144, 0x800, v0
	v_add_u32_e32 v145, 0xc00, v0
	ds_read_b64 v[130:131], v142
	ds_read2_b64 v[66:69], v0 offset0:33 offset1:66
	ds_read2_b64 v[72:75], v0 offset0:99 offset1:132
	ds_read2_b64 v[76:79], v0 offset0:165 offset1:198
	ds_read2_b64 v[80:83], v143 offset0:103 offset1:136
	ds_read2_b64 v[84:87], v144 offset0:41 offset1:74
	ds_read2_b64 v[88:91], v144 offset0:107 offset1:140
	ds_read2_b64 v[92:95], v144 offset0:173 offset1:206
	ds_read2_b64 v[96:99], v145 offset0:111 offset1:144
	v_add_u32_e32 v146, 0x1000, v0
	ds_read2_b64 v[100:103], v146 offset0:49 offset1:82
	ds_read2_b64 v[106:109], v146 offset0:115 offset1:148
	ds_read2_b64 v[110:113], v146 offset0:181 offset1:214
	v_add_u32_e32 v147, 0x1400, v0
	ds_read2_b64 v[114:117], v147 offset0:119 offset1:152
	s_waitcnt lgkmcnt(4)
	v_pk_add_f32 v[134:135], v[130:131], v[98:99]
	v_pk_add_f32 v[98:99], v[130:131], v[98:99] neg_lo:[0,1] neg_hi:[0,1]
	s_waitcnt lgkmcnt(3)
	v_pk_add_f32 v[130:131], v[66:67], v[100:101]
	v_pk_add_f32 v[66:67], v[66:67], v[100:101] neg_lo:[0,1] neg_hi:[0,1]
	v_add_u32_e32 v70, 0x1800, v0
	v_pk_mul_f32 v[100:101], v[66:67], s[50:51]
	ds_read2_b64 v[118:121], v70 offset0:57 offset1:90
	ds_read2_b64 v[122:125], v70 offset0:123 offset1:156
	ds_read2_b64 v[126:129], v70 offset0:189 offset1:222
	ds_read_b64 v[132:133], v0 offset:8184
	v_pk_fma_f32 v[66:67], v[66:67], s[20:21], v[100:101] op_sel:[0,0,1] op_sel_hi:[1,0,0]
	v_pk_add_f32 v[100:101], v[68:69], v[102:103]
	v_pk_add_f32 v[68:69], v[68:69], v[102:103] neg_lo:[0,1] neg_hi:[0,1]
	v_mul_lo_u32 v105, v140, v105
	v_pk_mul_f32 v[102:103], v[68:69], s[14:15]
	v_cvt_f32_i32_e32 v105, v105
	v_pk_fma_f32 v[68:69], v[68:69], s[6:7], v[102:103] op_sel:[0,0,1] op_sel_hi:[1,0,0]
	s_waitcnt lgkmcnt(6)
	v_pk_add_f32 v[102:103], v[72:73], v[106:107]
	v_pk_add_f32 v[72:73], v[72:73], v[106:107] neg_lo:[0,1] neg_hi:[0,1]
	v_and_b32_e32 v71, 0xffffffe0, v71
	v_pk_mul_f32 v[106:107], v[72:73], s[52:53]
	v_cvt_f32_i32_e32 v71, v71
	v_pk_fma_f32 v[72:73], v[72:73], s[24:25], v[106:107] op_sel:[0,0,1] op_sel_hi:[1,0,0]
	v_pk_add_f32 v[106:107], v[74:75], v[108:109]
	v_pk_add_f32 v[74:75], v[74:75], v[108:109] neg_lo:[0,1] neg_hi:[0,1]
	v_mul_f32_e32 v71, 0x38800000, v71
	v_pk_mul_f32 v[108:109], v[74:75], s[10:11]
	s_nop 0
	v_pk_fma_f32 v[74:75], v[74:75], s[10:11], v[108:109] op_sel:[0,0,1] op_sel_hi:[1,0,0]
	s_waitcnt lgkmcnt(5)
	v_pk_add_f32 v[108:109], v[76:77], v[110:111]
	v_pk_add_f32 v[76:77], v[76:77], v[110:111] neg_lo:[0,1] neg_hi:[0,1]
	v_pk_mul_f32 v[110:111], v[76:77], s[24:25]
	v_pk_fma_f32 v[76:77], v[76:77], s[0:1], v[110:111] op_sel:[0,0,1] op_sel_hi:[1,0,0]
	v_pk_add_f32 v[110:111], v[78:79], v[112:113]
	v_pk_add_f32 v[78:79], v[78:79], v[112:113] neg_lo:[0,1] neg_hi:[0,1]
	v_pk_mul_f32 v[112:113], v[78:79], s[6:7]
	v_pk_fma_f32 v[78:79], v[78:79], s[14:15], v[112:113] op_sel:[0,0,1] op_sel_hi:[1,0,0]
	s_waitcnt lgkmcnt(4)
	v_pk_add_f32 v[112:113], v[80:81], v[114:115]
	v_pk_add_f32 v[80:81], v[80:81], v[114:115] neg_lo:[0,1] neg_hi:[0,1]
	v_pk_mul_f32 v[114:115], v[80:81], s[20:21]
	v_pk_fma_f32 v[80:81], v[80:81], s[48:49], v[114:115] op_sel:[0,0,1] op_sel_hi:[1,0,0]
	v_pk_add_f32 v[114:115], v[82:83], v[116:117]
	v_pk_add_f32 v[116:117], v[82:83], v[116:117] op_sel:[1,1] op_sel_hi:[0,0] neg_lo:[1,0] neg_hi:[0,1]
	s_mov_b64 s[48:49], -1
	s_waitcnt lgkmcnt(3)
	v_pk_add_f32 v[82:83], v[84:85], v[118:119]
	v_pk_add_f32 v[84:85], v[84:85], v[118:119] neg_lo:[0,1] neg_hi:[0,1]
	v_pk_mul_f32 v[118:119], v[84:85], s[20:21]
	v_pk_fma_f32 v[84:85], v[84:85], s[18:19], v[118:119] op_sel:[0,0,1] op_sel_hi:[1,0,0]
	v_pk_add_f32 v[118:119], v[86:87], v[120:121]
	v_pk_add_f32 v[86:87], v[86:87], v[120:121] neg_lo:[0,1] neg_hi:[0,1]
	v_pk_mul_f32 v[120:121], v[86:87], s[6:7]
	v_pk_fma_f32 v[86:87], v[86:87], s[4:5], v[120:121] op_sel:[0,0,1] op_sel_hi:[1,0,0]
	s_waitcnt lgkmcnt(2)
	v_pk_add_f32 v[120:121], v[88:89], v[122:123]
	v_pk_add_f32 v[88:89], v[88:89], v[122:123] neg_lo:[0,1] neg_hi:[0,1]
	v_pk_mul_f32 v[122:123], v[88:89], s[24:25]
	v_pk_fma_f32 v[88:89], v[88:89], s[22:23], v[122:123] op_sel:[0,0,1] op_sel_hi:[1,0,0]
	v_pk_add_f32 v[122:123], v[90:91], v[124:125]
	v_pk_add_f32 v[90:91], v[90:91], v[124:125] neg_lo:[0,1] neg_hi:[0,1]
	v_pk_mul_f32 v[124:125], v[90:91], s[10:11]
	v_pk_fma_f32 v[90:91], v[90:91], s[8:9], v[124:125] op_sel:[0,0,1] op_sel_hi:[1,0,0]
	s_waitcnt lgkmcnt(1)
	v_pk_add_f32 v[124:125], v[92:93], v[126:127]
	v_pk_add_f32 v[92:93], v[92:93], v[126:127] neg_lo:[0,1] neg_hi:[0,1]
	v_pk_mul_f32 v[126:127], v[92:93], s[52:53]
	v_pk_fma_f32 v[92:93], v[92:93], s[26:27], v[126:127] op_sel:[0,0,1] op_sel_hi:[1,0,0]
	v_pk_add_f32 v[126:127], v[94:95], v[128:129]
	v_pk_add_f32 v[94:95], v[94:95], v[128:129] neg_lo:[0,1] neg_hi:[0,1]
	v_pk_mul_f32 v[128:129], v[94:95], s[14:15]
	v_pk_fma_f32 v[94:95], v[94:95], s[12:13], v[128:129] op_sel:[0,0,1] op_sel_hi:[1,0,0]
	s_waitcnt lgkmcnt(0)
	v_pk_add_f32 v[128:129], v[96:97], v[132:133]
	v_pk_add_f32 v[96:97], v[96:97], v[132:133] neg_lo:[0,1] neg_hi:[0,1]
	v_pk_mul_f32 v[132:133], v[96:97], s[50:51]
	v_pk_fma_f32 v[96:97], v[96:97], s[34:35], v[132:133] op_sel:[0,0,1] op_sel_hi:[1,0,0]
	v_pk_add_f32 v[132:133], v[134:135], v[114:115]
	v_pk_add_f32 v[114:115], v[134:135], v[114:115] neg_lo:[0,1] neg_hi:[0,1]
	v_pk_add_f32 v[134:135], v[130:131], v[82:83]
	v_pk_add_f32 v[82:83], v[130:131], v[82:83] neg_lo:[0,1] neg_hi:[0,1]
	v_pk_mul_f32 v[130:131], v[82:83], s[14:15]
	v_pk_fma_f32 v[82:83], v[82:83], s[6:7], v[130:131] op_sel:[0,0,1] op_sel_hi:[1,0,0]
	v_pk_add_f32 v[130:131], v[100:101], v[118:119]
	v_pk_add_f32 v[100:101], v[100:101], v[118:119] neg_lo:[0,1] neg_hi:[0,1]
	v_pk_mul_f32 v[118:119], v[100:101], s[10:11]
	v_pk_fma_f32 v[100:101], v[100:101], s[10:11], v[118:119] op_sel:[0,0,1] op_sel_hi:[1,0,0]
	v_pk_add_f32 v[118:119], v[102:103], v[120:121]
	v_pk_add_f32 v[102:103], v[102:103], v[120:121] neg_lo:[0,1] neg_hi:[0,1]
	v_pk_mul_f32 v[120:121], v[102:103], s[6:7]
	v_pk_fma_f32 v[102:103], v[102:103], s[14:15], v[120:121] op_sel:[0,0,1] op_sel_hi:[1,0,0]
	v_pk_add_f32 v[120:121], v[106:107], v[122:123]
	v_pk_add_f32 v[122:123], v[106:107], v[122:123] op_sel:[1,1] op_sel_hi:[0,0] neg_lo:[1,0] neg_hi:[0,1]
	v_pk_add_f32 v[106:107], v[108:109], v[124:125]
	v_pk_add_f32 v[108:109], v[108:109], v[124:125] neg_lo:[0,1] neg_hi:[0,1]
	v_pk_mul_f32 v[124:125], v[108:109], s[6:7]
	v_pk_fma_f32 v[108:109], v[108:109], s[4:5], v[124:125] op_sel:[0,0,1] op_sel_hi:[1,0,0]
	v_pk_add_f32 v[124:125], v[110:111], v[126:127]
	v_pk_add_f32 v[110:111], v[110:111], v[126:127] neg_lo:[0,1] neg_hi:[0,1]
	v_pk_mul_f32 v[126:127], v[110:111], s[10:11]
	v_pk_fma_f32 v[110:111], v[110:111], s[8:9], v[126:127] op_sel:[0,0,1] op_sel_hi:[1,0,0]
	v_pk_add_f32 v[126:127], v[112:113], v[128:129]
	v_pk_add_f32 v[112:113], v[112:113], v[128:129] neg_lo:[0,1] neg_hi:[0,1]
	v_pk_mul_f32 v[128:129], v[112:113], s[14:15]
	v_pk_fma_f32 v[112:113], v[112:113], s[12:13], v[128:129] op_sel:[0,0,1] op_sel_hi:[1,0,0]
	v_pk_add_f32 v[128:129], v[98:99], v[116:117]
	v_pk_add_f32 v[98:99], v[98:99], v[116:117] neg_lo:[0,1] neg_hi:[0,1]
	v_pk_add_f32 v[116:117], v[66:67], v[84:85]
	v_pk_add_f32 v[66:67], v[66:67], v[84:85] neg_lo:[0,1] neg_hi:[0,1]
	v_pk_mul_f32 v[84:85], v[66:67], s[14:15]
	v_pk_fma_f32 v[66:67], v[66:67], s[6:7], v[84:85] op_sel:[0,0,1] op_sel_hi:[1,0,0]
	v_pk_add_f32 v[84:85], v[68:69], v[86:87]
	v_pk_add_f32 v[68:69], v[68:69], v[86:87] neg_lo:[0,1] neg_hi:[0,1]
	v_pk_mul_f32 v[86:87], v[68:69], s[10:11]
	v_pk_fma_f32 v[68:69], v[68:69], s[10:11], v[86:87] op_sel:[0,0,1] op_sel_hi:[1,0,0]
	v_pk_add_f32 v[86:87], v[72:73], v[88:89]
	v_pk_add_f32 v[72:73], v[72:73], v[88:89] neg_lo:[0,1] neg_hi:[0,1]
	v_pk_mul_f32 v[88:89], v[72:73], s[6:7]
	v_pk_fma_f32 v[72:73], v[72:73], s[14:15], v[88:89] op_sel:[0,0,1] op_sel_hi:[1,0,0]
	v_pk_add_f32 v[88:89], v[74:75], v[90:91]
	v_pk_add_f32 v[90:91], v[74:75], v[90:91] op_sel:[1,1] op_sel_hi:[0,0] neg_lo:[1,0] neg_hi:[0,1]
	v_pk_add_f32 v[74:75], v[76:77], v[92:93]
	v_pk_add_f32 v[76:77], v[76:77], v[92:93] neg_lo:[0,1] neg_hi:[0,1]
	v_pk_mul_f32 v[92:93], v[76:77], s[6:7]
	v_pk_fma_f32 v[76:77], v[76:77], s[4:5], v[92:93] op_sel:[0,0,1] op_sel_hi:[1,0,0]
	v_pk_add_f32 v[92:93], v[78:79], v[94:95]
	v_pk_add_f32 v[78:79], v[78:79], v[94:95] neg_lo:[0,1] neg_hi:[0,1]
	s_mov_b32 s5, 0
	v_pk_mul_f32 v[94:95], v[78:79], s[10:11]
	v_pk_fma_f32 v[78:79], v[78:79], s[8:9], v[94:95] op_sel:[0,0,1] op_sel_hi:[1,0,0]
	v_pk_add_f32 v[94:95], v[80:81], v[96:97]
	v_pk_add_f32 v[80:81], v[80:81], v[96:97] neg_lo:[0,1] neg_hi:[0,1]
	v_pk_mul_f32 v[96:97], v[80:81], s[14:15]
	v_pk_fma_f32 v[80:81], v[80:81], s[12:13], v[96:97] op_sel:[0,0,1] op_sel_hi:[1,0,0]
	v_pk_add_f32 v[96:97], v[132:133], v[120:121]
	v_pk_add_f32 v[120:121], v[132:133], v[120:121] neg_lo:[0,1] neg_hi:[0,1]
	v_pk_add_f32 v[132:133], v[134:135], v[106:107]
	v_pk_add_f32 v[106:107], v[134:135], v[106:107] neg_lo:[0,1] neg_hi:[0,1]
	v_pk_mul_f32 v[134:135], v[106:107], s[10:11]
	v_pk_fma_f32 v[106:107], v[106:107], s[10:11], v[134:135] op_sel:[0,0,1] op_sel_hi:[1,0,0]
	v_pk_add_f32 v[134:135], v[130:131], v[124:125]
	v_pk_add_f32 v[130:131], v[130:131], v[124:125] op_sel:[1,1] op_sel_hi:[0,0] neg_lo:[1,0] neg_hi:[0,1]
	v_pk_add_f32 v[124:125], v[118:119], v[126:127]
	v_pk_add_f32 v[118:119], v[118:119], v[126:127] neg_lo:[0,1] neg_hi:[0,1]
	v_pk_mul_f32 v[126:127], v[118:119], s[10:11]
	v_pk_fma_f32 v[118:119], v[118:119], s[8:9], v[126:127] op_sel:[0,0,1] op_sel_hi:[1,0,0]
	v_pk_add_f32 v[126:127], v[114:115], v[122:123]
	v_pk_add_f32 v[114:115], v[114:115], v[122:123] neg_lo:[0,1] neg_hi:[0,1]
	v_pk_add_f32 v[122:123], v[82:83], v[108:109]
	v_pk_add_f32 v[82:83], v[82:83], v[108:109] neg_lo:[0,1] neg_hi:[0,1]
	v_pk_mul_f32 v[108:109], v[82:83], s[10:11]
	v_pk_fma_f32 v[82:83], v[82:83], s[10:11], v[108:109] op_sel:[0,0,1] op_sel_hi:[1,0,0]
	v_pk_add_f32 v[108:109], v[100:101], v[110:111]
	v_pk_add_f32 v[110:111], v[100:101], v[110:111] op_sel:[1,1] op_sel_hi:[0,0] neg_lo:[1,0] neg_hi:[0,1]
	v_pk_add_f32 v[100:101], v[102:103], v[112:113]
	v_pk_add_f32 v[102:103], v[102:103], v[112:113] neg_lo:[0,1] neg_hi:[0,1]
	v_pk_mul_f32 v[112:113], v[102:103], s[10:11]
	v_pk_fma_f32 v[102:103], v[102:103], s[8:9], v[112:113] op_sel:[0,0,1] op_sel_hi:[1,0,0]
	v_pk_add_f32 v[112:113], v[128:129], v[88:89]
	v_pk_add_f32 v[88:89], v[128:129], v[88:89] neg_lo:[0,1] neg_hi:[0,1]
	v_pk_add_f32 v[128:129], v[116:117], v[74:75]
	v_pk_add_f32 v[74:75], v[116:117], v[74:75] neg_lo:[0,1] neg_hi:[0,1]
	v_pk_mul_f32 v[116:117], v[74:75], s[10:11]
	v_pk_fma_f32 v[74:75], v[74:75], s[10:11], v[116:117] op_sel:[0,0,1] op_sel_hi:[1,0,0]
	v_pk_add_f32 v[116:117], v[84:85], v[92:93]
	v_pk_add_f32 v[92:93], v[84:85], v[92:93] op_sel:[1,1] op_sel_hi:[0,0] neg_lo:[1,0] neg_hi:[0,1]
	v_pk_add_f32 v[84:85], v[86:87], v[94:95]
	v_pk_add_f32 v[86:87], v[86:87], v[94:95] neg_lo:[0,1] neg_hi:[0,1]
	v_pk_mul_f32 v[94:95], v[86:87], s[10:11]
	v_pk_fma_f32 v[86:87], v[86:87], s[8:9], v[94:95] op_sel:[0,0,1] op_sel_hi:[1,0,0]
	v_pk_add_f32 v[94:95], v[98:99], v[90:91]
	v_pk_add_f32 v[90:91], v[98:99], v[90:91] neg_lo:[0,1] neg_hi:[0,1]
	v_pk_add_f32 v[98:99], v[66:67], v[76:77]
	v_pk_add_f32 v[66:67], v[66:67], v[76:77] neg_lo:[0,1] neg_hi:[0,1]
	v_pk_mul_f32 v[76:77], v[66:67], s[10:11]
	v_pk_fma_f32 v[66:67], v[66:67], s[10:11], v[76:77] op_sel:[0,0,1] op_sel_hi:[1,0,0]
	v_pk_add_f32 v[76:77], v[68:69], v[78:79]
	v_pk_add_f32 v[78:79], v[68:69], v[78:79] op_sel:[1,1] op_sel_hi:[0,0] neg_lo:[1,0] neg_hi:[0,1]
	v_pk_add_f32 v[68:69], v[72:73], v[80:81]
	v_pk_add_f32 v[72:73], v[72:73], v[80:81] neg_lo:[0,1] neg_hi:[0,1]
	v_pk_add_f32 v[136:137], v[90:91], v[78:79]
	v_pk_mul_f32 v[80:81], v[72:73], s[10:11]
	v_pk_add_f32 v[78:79], v[90:91], v[78:79] neg_lo:[0,1] neg_hi:[0,1]
	v_pk_fma_f32 v[72:73], v[72:73], s[8:9], v[80:81] op_sel:[0,0,1] op_sel_hi:[1,0,0]
	v_pk_add_f32 v[80:81], v[96:97], v[134:135]
	v_pk_add_f32 v[96:97], v[96:97], v[134:135] neg_lo:[0,1] neg_hi:[0,1]
	v_pk_add_f32 v[134:135], v[132:133], v[124:125]
	v_pk_add_f32 v[132:133], v[132:133], v[124:125] op_sel:[1,1] op_sel_hi:[0,0] neg_lo:[1,0] neg_hi:[0,1]
	v_pk_add_f32 v[90:91], v[66:67], v[72:73]
	v_pk_add_f32 v[124:125], v[120:121], v[130:131]
	v_pk_add_f32 v[120:121], v[120:121], v[130:131] neg_lo:[0,1] neg_hi:[0,1]
	v_pk_add_f32 v[130:131], v[106:107], v[118:119]
	v_pk_add_f32 v[118:119], v[106:107], v[118:119] op_sel:[1,1] op_sel_hi:[0,0] neg_lo:[1,0] neg_hi:[0,1]
	v_pk_add_f32 v[72:73], v[66:67], v[72:73] op_sel:[1,1] op_sel_hi:[0,0] neg_lo:[1,0] neg_hi:[0,1]
	v_pk_add_f32 v[106:107], v[126:127], v[108:109]
	v_pk_add_f32 v[108:109], v[126:127], v[108:109] neg_lo:[0,1] neg_hi:[0,1]
	v_pk_add_f32 v[126:127], v[122:123], v[100:101]
	v_pk_add_f32 v[122:123], v[122:123], v[100:101] op_sel:[1,1] op_sel_hi:[0,0] neg_lo:[1,0] neg_hi:[0,1]
	v_pk_add_f32 v[100:101], v[114:115], v[110:111]
	v_pk_add_f32 v[110:111], v[114:115], v[110:111] neg_lo:[0,1] neg_hi:[0,1]
	v_pk_add_f32 v[114:115], v[82:83], v[102:103]
	v_pk_add_f32 v[102:103], v[82:83], v[102:103] op_sel:[1,1] op_sel_hi:[0,0] neg_lo:[1,0] neg_hi:[0,1]
	v_pk_add_f32 v[82:83], v[112:113], v[116:117]
	v_pk_add_f32 v[112:113], v[112:113], v[116:117] neg_lo:[0,1] neg_hi:[0,1]
	v_pk_add_f32 v[116:117], v[128:129], v[84:85]
	v_pk_add_f32 v[128:129], v[128:129], v[84:85] op_sel:[1,1] op_sel_hi:[0,0] neg_lo:[1,0] neg_hi:[0,1]
	v_pk_add_f32 v[138:139], v[80:81], v[134:135]
	v_pk_add_f32 v[84:85], v[88:89], v[92:93]
	v_pk_add_f32 v[88:89], v[88:89], v[92:93] neg_lo:[0,1] neg_hi:[0,1]
	v_pk_add_f32 v[92:93], v[74:75], v[86:87]
	v_pk_add_f32 v[86:87], v[74:75], v[86:87] op_sel:[1,1] op_sel_hi:[0,0] neg_lo:[1,0] neg_hi:[0,1]
	v_pk_add_f32 v[80:81], v[80:81], v[134:135] neg_lo:[0,1] neg_hi:[0,1]
	v_pk_add_f32 v[74:75], v[94:95], v[76:77]
	v_pk_add_f32 v[76:77], v[94:95], v[76:77] neg_lo:[0,1] neg_hi:[0,1]
	v_pk_add_f32 v[94:95], v[98:99], v[68:69]
	v_pk_add_f32 v[98:99], v[98:99], v[68:69] op_sel:[1,1] op_sel_hi:[0,0] neg_lo:[1,0] neg_hi:[0,1]
	v_pk_add_f32 v[134:135], v[96:97], v[132:133]
	v_pk_add_f32 v[96:97], v[96:97], v[132:133] neg_lo:[0,1] neg_hi:[0,1]
	v_pk_add_f32 v[132:133], v[124:125], v[130:131]
	v_pk_add_f32 v[124:125], v[124:125], v[130:131] neg_lo:[0,1] neg_hi:[0,1]
	v_pk_add_f32 v[130:131], v[120:121], v[118:119]
	v_pk_add_f32 v[68:69], v[120:121], v[118:119] neg_lo:[0,1] neg_hi:[0,1]
	v_pk_add_f32 v[118:119], v[106:107], v[126:127]
	v_pk_add_f32 v[106:107], v[106:107], v[126:127] neg_lo:[0,1] neg_hi:[0,1]
	v_pk_add_f32 v[126:127], v[78:79], v[72:73]
	v_pk_add_f32 v[72:73], v[78:79], v[72:73] neg_lo:[0,1] neg_hi:[0,1]
	v_mul_f32_e32 v78, 0x38800000, v105
	v_sin_f32_e32 v79, v78
	v_cos_f32_e32 v78, v78
	v_pk_add_f32 v[120:121], v[108:109], v[122:123]
	v_pk_add_f32 v[108:109], v[108:109], v[122:123] neg_lo:[0,1] neg_hi:[0,1]
	v_pk_add_f32 v[122:123], v[100:101], v[114:115]
	v_pk_add_f32 v[100:101], v[100:101], v[114:115] neg_lo:[0,1] neg_hi:[0,1]
	v_pk_add_f32 v[114:115], v[110:111], v[102:103]
	v_pk_add_f32 v[66:67], v[110:111], v[102:103] neg_lo:[0,1] neg_hi:[0,1]
	v_pk_add_f32 v[102:103], v[82:83], v[116:117]
	v_pk_add_f32 v[82:83], v[82:83], v[116:117] neg_lo:[0,1] neg_hi:[0,1]
	v_pk_add_f32 v[116:117], v[84:85], v[92:93]
	v_pk_add_f32 v[84:85], v[84:85], v[92:93] neg_lo:[0,1] neg_hi:[0,1]
	v_pk_add_f32 v[92:93], v[88:89], v[86:87]
	v_pk_add_f32 v[86:87], v[88:89], v[86:87] neg_lo:[0,1] neg_hi:[0,1]
	v_pk_add_f32 v[88:89], v[74:75], v[94:95]
	v_pk_add_f32 v[74:75], v[74:75], v[94:95] neg_lo:[0,1] neg_hi:[0,1]
	v_pk_add_f32 v[94:95], v[76:77], v[98:99]
	v_pk_add_f32 v[76:77], v[76:77], v[98:99] neg_lo:[0,1] neg_hi:[0,1]
	v_pk_add_f32 v[98:99], v[136:137], v[90:91]
	v_pk_add_f32 v[90:91], v[136:137], v[90:91] neg_lo:[0,1] neg_hi:[0,1]
	v_sin_f32_e32 v136, v71
	v_pk_add_f32 v[110:111], v[112:113], v[128:129]
	v_pk_add_f32 v[112:113], v[112:113], v[128:129] neg_lo:[0,1] neg_hi:[0,1]
	v_cos_f32_e32 v128, v71
	v_pk_mul_f32 v[140:141], v[138:139], v[78:79] op_sel:[1,1] op_sel_hi:[0,1] neg_lo:[0,1]
	s_nop 0
	v_pk_fma_f32 v[138:139], v[138:139], v[78:79], v[140:141] op_sel_hi:[1,0,1]
	ds_write_b64 v142, v[138:139]
	v_pk_mul_f32 v[138:139], v[136:137], v[78:79] op_sel:[0,1] op_sel_hi:[0,0] neg_lo:[1,0]
	v_pk_fma_f32 v[78:79], v[78:79], v[128:129], v[138:139] op_sel_hi:[1,0,1]
	v_pk_mul_f32 v[138:139], v[102:103], v[78:79] op_sel:[1,1] op_sel_hi:[0,1] neg_lo:[0,1]
	v_pk_fma_f32 v[102:103], v[102:103], v[78:79], v[138:139] op_sel_hi:[1,0,1]
	v_pk_mul_f32 v[138:139], v[136:137], v[78:79] op_sel:[0,1] op_sel_hi:[0,0] neg_lo:[1,0]
	v_pk_fma_f32 v[78:79], v[78:79], v[128:129], v[138:139] op_sel_hi:[1,0,1]
	v_pk_mul_f32 v[138:139], v[118:119], v[78:79] op_sel:[1,1] op_sel_hi:[0,1] neg_lo:[0,1]
	v_pk_fma_f32 v[118:119], v[118:119], v[78:79], v[138:139] op_sel_hi:[1,0,1]
	ds_write2_b64 v0, v[102:103], v[118:119] offset0:33 offset1:66
	v_pk_mul_f32 v[102:103], v[136:137], v[78:79] op_sel:[0,1] op_sel_hi:[0,0] neg_lo:[1,0]
	v_pk_fma_f32 v[78:79], v[78:79], v[128:129], v[102:103] op_sel_hi:[1,0,1]
	v_pk_mul_f32 v[102:103], v[88:89], v[78:79] op_sel:[1,1] op_sel_hi:[0,1] neg_lo:[0,1]
	v_pk_fma_f32 v[88:89], v[88:89], v[78:79], v[102:103] op_sel_hi:[1,0,1]
	v_pk_mul_f32 v[102:103], v[136:137], v[78:79] op_sel:[0,1] op_sel_hi:[0,0] neg_lo:[1,0]
	v_pk_fma_f32 v[78:79], v[78:79], v[128:129], v[102:103] op_sel_hi:[1,0,1]
	v_pk_mul_f32 v[102:103], v[132:133], v[78:79] op_sel:[1,1] op_sel_hi:[0,1] neg_lo:[0,1]
	v_pk_fma_f32 v[102:103], v[132:133], v[78:79], v[102:103] op_sel_hi:[1,0,1]
	ds_write2_b64 v0, v[88:89], v[102:103] offset0:99 offset1:132
	v_pk_mul_f32 v[88:89], v[136:137], v[78:79] op_sel:[0,1] op_sel_hi:[0,0] neg_lo:[1,0]
	v_pk_fma_f32 v[78:79], v[78:79], v[128:129], v[88:89] op_sel_hi:[1,0,1]
	v_pk_mul_f32 v[88:89], v[116:117], v[78:79] op_sel:[1,1] op_sel_hi:[0,1] neg_lo:[0,1]
	v_pk_mul_f32 v[102:103], v[136:137], v[78:79] op_sel:[0,1] op_sel_hi:[0,0] neg_lo:[1,0]
	v_pk_fma_f32 v[88:89], v[116:117], v[78:79], v[88:89] op_sel_hi:[1,0,1]
	v_pk_fma_f32 v[78:79], v[78:79], v[128:129], v[102:103] op_sel_hi:[1,0,1]
	v_pk_mul_f32 v[102:103], v[122:123], v[78:79] op_sel:[1,1] op_sel_hi:[0,1] neg_lo:[0,1]
	v_pk_fma_f32 v[102:103], v[122:123], v[78:79], v[102:103] op_sel_hi:[1,0,1]
	ds_write2_b64 v0, v[88:89], v[102:103] offset0:165 offset1:198
	v_pk_mul_f32 v[88:89], v[136:137], v[78:79] op_sel:[0,1] op_sel_hi:[0,0] neg_lo:[1,0]
	v_pk_fma_f32 v[78:79], v[78:79], v[128:129], v[88:89] op_sel_hi:[1,0,1]
	v_pk_mul_f32 v[88:89], v[98:99], v[78:79] op_sel:[1,1] op_sel_hi:[0,1] neg_lo:[0,1]
	v_pk_fma_f32 v[88:89], v[98:99], v[78:79], v[88:89] op_sel_hi:[1,0,1]
	v_pk_mul_f32 v[98:99], v[136:137], v[78:79] op_sel:[0,1] op_sel_hi:[0,0] neg_lo:[1,0]
	v_pk_fma_f32 v[78:79], v[78:79], v[128:129], v[98:99] op_sel_hi:[1,0,1]
	v_pk_mul_f32 v[98:99], v[134:135], v[78:79] op_sel:[1,1] op_sel_hi:[0,1] neg_lo:[0,1]
	v_pk_fma_f32 v[98:99], v[134:135], v[78:79], v[98:99] op_sel_hi:[1,0,1]
	ds_write2_b64 v143, v[88:89], v[98:99] offset0:103 offset1:136
	v_pk_mul_f32 v[88:89], v[136:137], v[78:79] op_sel:[0,1] op_sel_hi:[0,0] neg_lo:[1,0]
	v_pk_fma_f32 v[78:79], v[78:79], v[128:129], v[88:89] op_sel_hi:[1,0,1]
	v_pk_mul_f32 v[88:89], v[110:111], v[78:79] op_sel:[1,1] op_sel_hi:[0,1] neg_lo:[0,1]
	v_pk_mul_f32 v[98:99], v[136:137], v[78:79] op_sel:[0,1] op_sel_hi:[0,0] neg_lo:[1,0]
	v_pk_fma_f32 v[88:89], v[110:111], v[78:79], v[88:89] op_sel_hi:[1,0,1]
	v_pk_fma_f32 v[78:79], v[78:79], v[128:129], v[98:99] op_sel_hi:[1,0,1]
	v_pk_mul_f32 v[98:99], v[120:121], v[78:79] op_sel:[1,1] op_sel_hi:[0,1] neg_lo:[0,1]
	v_pk_fma_f32 v[98:99], v[120:121], v[78:79], v[98:99] op_sel_hi:[1,0,1]
	ds_write2_b64 v144, v[88:89], v[98:99] offset0:41 offset1:74
	v_pk_mul_f32 v[88:89], v[136:137], v[78:79] op_sel:[0,1] op_sel_hi:[0,0] neg_lo:[1,0]
	v_pk_fma_f32 v[78:79], v[78:79], v[128:129], v[88:89] op_sel_hi:[1,0,1]
	v_pk_mul_f32 v[88:89], v[94:95], v[78:79] op_sel:[1,1] op_sel_hi:[0,1] neg_lo:[0,1]
	v_pk_fma_f32 v[88:89], v[94:95], v[78:79], v[88:89] op_sel_hi:[1,0,1]
	v_pk_mul_f32 v[94:95], v[136:137], v[78:79] op_sel:[0,1] op_sel_hi:[0,0] neg_lo:[1,0]
	v_pk_fma_f32 v[78:79], v[78:79], v[128:129], v[94:95] op_sel_hi:[1,0,1]
	v_pk_mul_f32 v[94:95], v[130:131], v[78:79] op_sel:[1,1] op_sel_hi:[0,1] neg_lo:[0,1]
	v_pk_fma_f32 v[94:95], v[130:131], v[78:79], v[94:95] op_sel_hi:[1,0,1]
	ds_write2_b64 v144, v[88:89], v[94:95] offset0:107 offset1:140
	v_pk_mul_f32 v[88:89], v[136:137], v[78:79] op_sel:[0,1] op_sel_hi:[0,0] neg_lo:[1,0]
	v_pk_fma_f32 v[78:79], v[78:79], v[128:129], v[88:89] op_sel_hi:[1,0,1]
	v_pk_mul_f32 v[88:89], v[92:93], v[78:79] op_sel:[1,1] op_sel_hi:[0,1] neg_lo:[0,1]
	v_pk_fma_f32 v[88:89], v[92:93], v[78:79], v[88:89] op_sel_hi:[1,0,1]
	v_pk_mul_f32 v[92:93], v[136:137], v[78:79] op_sel:[0,1] op_sel_hi:[0,0] neg_lo:[1,0]
	v_pk_fma_f32 v[78:79], v[78:79], v[128:129], v[92:93] op_sel_hi:[1,0,1]
	v_pk_mul_f32 v[92:93], v[114:115], v[78:79] op_sel:[1,1] op_sel_hi:[0,1] neg_lo:[0,1]
	v_pk_fma_f32 v[92:93], v[114:115], v[78:79], v[92:93] op_sel_hi:[1,0,1]
	ds_write2_b64 v144, v[88:89], v[92:93] offset0:173 offset1:206
	v_pk_mul_f32 v[88:89], v[136:137], v[78:79] op_sel:[0,1] op_sel_hi:[0,0] neg_lo:[1,0]
	v_pk_fma_f32 v[78:79], v[78:79], v[128:129], v[88:89] op_sel_hi:[1,0,1]
	v_pk_mul_f32 v[88:89], v[126:127], v[78:79] op_sel:[1,1] op_sel_hi:[0,1] neg_lo:[0,1]
	v_pk_mul_f32 v[92:93], v[136:137], v[78:79] op_sel:[0,1] op_sel_hi:[0,0] neg_lo:[1,0]
	v_pk_fma_f32 v[88:89], v[126:127], v[78:79], v[88:89] op_sel_hi:[1,0,1]
	v_pk_fma_f32 v[78:79], v[78:79], v[128:129], v[92:93] op_sel_hi:[1,0,1]
	v_pk_mul_f32 v[92:93], v[80:81], v[78:79] op_sel:[1,1] op_sel_hi:[0,1] neg_lo:[0,1]
	v_pk_fma_f32 v[80:81], v[80:81], v[78:79], v[92:93] op_sel_hi:[1,0,1]
	ds_write2_b64 v145, v[88:89], v[80:81] offset0:111 offset1:144
	v_pk_mul_f32 v[80:81], v[136:137], v[78:79] op_sel:[0,1] op_sel_hi:[0,0] neg_lo:[1,0]
	v_pk_fma_f32 v[78:79], v[78:79], v[128:129], v[80:81] op_sel_hi:[1,0,1]
	v_pk_mul_f32 v[80:81], v[82:83], v[78:79] op_sel:[1,1] op_sel_hi:[0,1] neg_lo:[0,1]
	v_pk_fma_f32 v[80:81], v[82:83], v[78:79], v[80:81] op_sel_hi:[1,0,1]
	v_pk_mul_f32 v[82:83], v[136:137], v[78:79] op_sel:[0,1] op_sel_hi:[0,0] neg_lo:[1,0]
	v_pk_fma_f32 v[78:79], v[78:79], v[128:129], v[82:83] op_sel_hi:[1,0,1]
	v_pk_mul_f32 v[82:83], v[106:107], v[78:79] op_sel:[1,1] op_sel_hi:[0,1] neg_lo:[0,1]
	v_pk_fma_f32 v[82:83], v[106:107], v[78:79], v[82:83] op_sel_hi:[1,0,1]
	ds_write2_b64 v146, v[80:81], v[82:83] offset0:49 offset1:82
	v_pk_mul_f32 v[80:81], v[136:137], v[78:79] op_sel:[0,1] op_sel_hi:[0,0] neg_lo:[1,0]
	v_pk_fma_f32 v[78:79], v[78:79], v[128:129], v[80:81] op_sel_hi:[1,0,1]
	v_pk_mul_f32 v[80:81], v[74:75], v[78:79] op_sel:[1,1] op_sel_hi:[0,1] neg_lo:[0,1]
	v_pk_fma_f32 v[74:75], v[74:75], v[78:79], v[80:81] op_sel_hi:[1,0,1]
	v_pk_mul_f32 v[80:81], v[136:137], v[78:79] op_sel:[0,1] op_sel_hi:[0,0] neg_lo:[1,0]
	v_pk_fma_f32 v[78:79], v[78:79], v[128:129], v[80:81] op_sel_hi:[1,0,1]
	v_pk_mul_f32 v[80:81], v[124:125], v[78:79] op_sel:[1,1] op_sel_hi:[0,1] neg_lo:[0,1]
	v_pk_fma_f32 v[80:81], v[124:125], v[78:79], v[80:81] op_sel_hi:[1,0,1]
	ds_write2_b64 v146, v[74:75], v[80:81] offset0:115 offset1:148
	v_pk_mul_f32 v[74:75], v[136:137], v[78:79] op_sel:[0,1] op_sel_hi:[0,0] neg_lo:[1,0]
	v_pk_fma_f32 v[74:75], v[78:79], v[128:129], v[74:75] op_sel_hi:[1,0,1]
	v_pk_mul_f32 v[78:79], v[84:85], v[74:75] op_sel:[1,1] op_sel_hi:[0,1] neg_lo:[0,1]
	v_pk_mul_f32 v[80:81], v[136:137], v[74:75] op_sel:[0,1] op_sel_hi:[0,0] neg_lo:[1,0]
	v_pk_fma_f32 v[78:79], v[84:85], v[74:75], v[78:79] op_sel_hi:[1,0,1]
	v_pk_fma_f32 v[74:75], v[74:75], v[128:129], v[80:81] op_sel_hi:[1,0,1]
	v_pk_mul_f32 v[80:81], v[100:101], v[74:75] op_sel:[1,1] op_sel_hi:[0,1] neg_lo:[0,1]
	v_pk_fma_f32 v[80:81], v[100:101], v[74:75], v[80:81] op_sel_hi:[1,0,1]
	ds_write2_b64 v146, v[78:79], v[80:81] offset0:181 offset1:214
	v_pk_mul_f32 v[78:79], v[136:137], v[74:75] op_sel:[0,1] op_sel_hi:[0,0] neg_lo:[1,0]
	v_pk_fma_f32 v[74:75], v[74:75], v[128:129], v[78:79] op_sel_hi:[1,0,1]
	v_pk_mul_f32 v[78:79], v[90:91], v[74:75] op_sel:[1,1] op_sel_hi:[0,1] neg_lo:[0,1]
	v_pk_mul_f32 v[80:81], v[136:137], v[74:75] op_sel:[0,1] op_sel_hi:[0,0] neg_lo:[1,0]
	v_pk_fma_f32 v[78:79], v[90:91], v[74:75], v[78:79] op_sel_hi:[1,0,1]
	v_pk_fma_f32 v[74:75], v[74:75], v[128:129], v[80:81] op_sel_hi:[1,0,1]
	v_pk_mul_f32 v[80:81], v[96:97], v[74:75] op_sel:[1,1] op_sel_hi:[0,1] neg_lo:[0,1]
	v_pk_fma_f32 v[80:81], v[96:97], v[74:75], v[80:81] op_sel_hi:[1,0,1]
	ds_write2_b64 v147, v[78:79], v[80:81] offset0:119 offset1:152
	v_pk_mul_f32 v[78:79], v[136:137], v[74:75] op_sel:[0,1] op_sel_hi:[0,0] neg_lo:[1,0]
	v_pk_fma_f32 v[74:75], v[74:75], v[128:129], v[78:79] op_sel_hi:[1,0,1]
	v_pk_mul_f32 v[78:79], v[112:113], v[74:75] op_sel:[1,1] op_sel_hi:[0,1] neg_lo:[0,1]
	v_pk_mul_f32 v[80:81], v[136:137], v[74:75] op_sel:[0,1] op_sel_hi:[0,0] neg_lo:[1,0]
	v_pk_fma_f32 v[78:79], v[112:113], v[74:75], v[78:79] op_sel_hi:[1,0,1]
	v_pk_fma_f32 v[74:75], v[74:75], v[128:129], v[80:81] op_sel_hi:[1,0,1]
	v_pk_mul_f32 v[80:81], v[108:109], v[74:75] op_sel:[1,1] op_sel_hi:[0,1] neg_lo:[0,1]
	v_pk_fma_f32 v[80:81], v[108:109], v[74:75], v[80:81] op_sel_hi:[1,0,1]
	ds_write2_b64 v70, v[78:79], v[80:81] offset0:57 offset1:90
	v_pk_mul_f32 v[78:79], v[136:137], v[74:75] op_sel:[0,1] op_sel_hi:[0,0] neg_lo:[1,0]
	v_pk_fma_f32 v[74:75], v[74:75], v[128:129], v[78:79] op_sel_hi:[1,0,1]
	v_pk_mul_f32 v[78:79], v[76:77], v[74:75] op_sel:[1,1] op_sel_hi:[0,1] neg_lo:[0,1]
	v_pk_fma_f32 v[76:77], v[76:77], v[74:75], v[78:79] op_sel_hi:[1,0,1]
	v_pk_mul_f32 v[78:79], v[136:137], v[74:75] op_sel:[0,1] op_sel_hi:[0,0] neg_lo:[1,0]
	v_pk_fma_f32 v[74:75], v[74:75], v[128:129], v[78:79] op_sel_hi:[1,0,1]
	v_pk_mul_f32 v[78:79], v[68:69], v[74:75] op_sel:[1,1] op_sel_hi:[0,1] neg_lo:[0,1]
	v_pk_fma_f32 v[68:69], v[68:69], v[74:75], v[78:79] op_sel_hi:[1,0,1]
	ds_write2_b64 v70, v[76:77], v[68:69] offset0:123 offset1:156
	v_pk_mul_f32 v[68:69], v[136:137], v[74:75] op_sel:[0,1] op_sel_hi:[0,0] neg_lo:[1,0]
	v_pk_fma_f32 v[68:69], v[74:75], v[128:129], v[68:69] op_sel_hi:[1,0,1]
	v_pk_mul_f32 v[74:75], v[86:87], v[68:69] op_sel:[1,1] op_sel_hi:[0,1] neg_lo:[0,1]
	v_pk_mul_f32 v[76:77], v[136:137], v[68:69] op_sel:[0,1] op_sel_hi:[0,0] neg_lo:[1,0]
	v_pk_fma_f32 v[74:75], v[86:87], v[68:69], v[74:75] op_sel_hi:[1,0,1]
	v_pk_fma_f32 v[68:69], v[68:69], v[128:129], v[76:77] op_sel_hi:[1,0,1]
	v_pk_mul_f32 v[76:77], v[66:67], v[68:69] op_sel:[1,1] op_sel_hi:[0,1] neg_lo:[0,1]
	v_pk_fma_f32 v[66:67], v[66:67], v[68:69], v[76:77] op_sel_hi:[1,0,1]
	ds_write2_b64 v70, v[74:75], v[66:67] offset0:189 offset1:222
	v_pk_mul_f32 v[66:67], v[136:137], v[68:69] op_sel:[0,1] op_sel_hi:[0,0] neg_lo:[1,0]
	v_pk_fma_f32 v[66:67], v[68:69], v[128:129], v[66:67] op_sel_hi:[1,0,1]
	v_pk_mul_f32 v[68:69], v[72:73], v[66:67] op_sel:[1,1] op_sel_hi:[0,1] neg_lo:[0,1]
	v_pk_fma_f32 v[66:67], v[72:73], v[66:67], v[68:69] op_sel_hi:[1,0,1]
	ds_write_b64 v0, v[66:67] offset:8184
	s_waitcnt lgkmcnt(0)
	s_barrier
